# MFMA-shadow half epilogue: last K-iteration peeled, the tile's final MFMA block (acc[1] only) carries the epilogue of the finished acc[0] half, one copy per column-block kind
# baseline (speedup 1.0000x reference)
; #define PG8_STAGE(bufoff, gbase, voff) do { _Pragma("unroll") for (int _i = 0; _i < 2; ++_i) \
;         __builtin_amdgcn_global_load_lds((const unsigned*)((const char*)(gbase) + (voff)[_i]), (PG8_LAS unsigned*)(lds + (bufoff) + ldsw + _i * 8192), 16, 0, 0); } while (0)
; #define PG8_LDA(dst, b, h) do { _Pragma("unroll") for (int m = 0; m < 4; ++m) _Pragma("unroll") for (int k = 0; k < 2; ++k) dst[m][k] = *(const PG8_LAS bf16x8*)(lds + PG8_SA(b, h) + aoff + m * 2048 + k * 1024); } while (0)
; #define PG8_LDB(dst, b, h) do { _Pragma("unroll") for (int n = 0; n < 2; ++n) _Pragma("unroll") for (int k = 0; k < 2; ++k) dst[n][k] = *(const PG8_LAS bf16x8*)(lds + PG8_SB(b, h) + boff + n * 2048 + k * 1024); } while (0)
; #define PG8_MMA(ai, bj, At, Bt) do { __builtin_amdgcn_s_setprio(1); _Pragma("unroll") for (int m = 0; m < 4; ++m) _Pragma("unroll") for (int n = 0; n < 2; ++n) _Pragma("unroll") for (int k = 0; k < 2; ++k) \
;         acc[ai][bj][m][n] = __builtin_amdgcn_mfma_f32_16x16x32_bf16(Bt[n][k], At[m][k], acc[ai][bj][m][n], 0, 0, 0); __builtin_amdgcn_s_setprio(0); } while (0)
; #define PG8_WAIT_V(n) asm volatile("s_waitcnt vmcnt(" #n ")" ::: "memory")
; #define PG8_WAIT_L(n) asm volatile("s_waitcnt lgkmcnt(" #n ")" ::: "memory")
; #define PG8_BAR __builtin_amdgcn_s_barrier()
; #define PG8_SCHED __builtin_amdgcn_sched_barrier(0)
; template <class Epi, class Sched, bool ALIGN_EPI = false, bool SP2 = false, bool RS = false, bool BPRE = false>
; __device__ __forceinline__ void gemm_phase(PG8_LAS unsigned char* lds, const Gemm g, const Sched& S, const Epi& E, const float* rs_ss = nullptr, PG8_LAS float* rs_tab = nullptr) {
;     ...
;             PG8_LDB(B0, 0, 0); PG8_LDB(B1, 0, 1); PG8_SCHED; PG8_LDA(At, 0, 0); PG8_STAGE(PG8_SA(1, 1), a1 + hstep, voffA);
;             PG8_WAIT_V(8); PG8_WAIT_L(0); PG8_BAR; PG8_MMA(0, 0, At, B0); PG8_MMA(0, 1, At, B1); PG8_BAR; PG8_SCHED;
;             PG8_LDA(At, 0, 1); PG8_STAGE(PG8_SB(0, 0), b2, voffB); PG8_STAGE(PG8_SB(0, 1), b2 + hstep, voffB); PG8_STAGE(PG8_SA(0, 0), a2, voffA);
;             PG8_WAIT_V(8); PG8_WAIT_L(0); PG8_BAR; PG8_MMA(1, 0, At, B0); PG8_MMA(1, 1, At, B1); PG8_BAR; PG8_SCHED;
.LBB0_196:
	ds_read_b128 v[130:133], v161
	ds_read_b128 v[134:137], v161 offset:1024
	ds_read_b128 v[152:155], v161 offset:2048
	ds_read_b128 v[156:159], v161 offset:3072
	ds_read_b128 v[166:169], v162
	ds_read_b128 v[170:173], v162 offset:1024
	ds_read_b128 v[174:177], v162 offset:2048
	ds_read_b128 v[182:185], v162 offset:3072
	s_add_u32 s58, s56, 0xfff84000
	s_addc_u32 s59, s57, -1
	s_cmp_eq_u32 s89, 28
	s_cselect_b32 s70, s19, s58
	s_cselect_b32 s71, s5, s59
	s_cselect_b32 s60, s47, s87
	s_cselect_b32 s61, s17, s88
	s_add_u32 s58, s70, 0x4000
	s_addc_u32 s59, s71, 0
	v_lshl_add_u64 v[178:179], s[56:57], 0, v[138:139]
	s_add_i32 m0, s72, 0xc000
	ds_read_b128 v[186:189], v163
	ds_read_b128 v[190:193], v163 offset:1024
	ds_read_b128 v[194:197], v163 offset:2048
	ds_read_b128 v[198:201], v163 offset:3072
	ds_read_b128 v[202:205], v163 offset:4096
	ds_read_b128 v[206:209], v163 offset:5120
	ds_read_b128 v[210:213], v163 offset:6144
	ds_read_b128 v[214:217], v163 offset:7168
	global_load_lds_dwordx4 v[178:179], off
	v_lshl_add_u64 v[178:179], s[56:57], 0, v[146:147]
	s_add_i32 m0, s72, 0xe000
	s_nop 0
	global_load_lds_dwordx4 v[178:179], off
	s_waitcnt vmcnt(8)
	s_waitcnt lgkmcnt(0)
	s_barrier
	s_setprio 1
	s_waitcnt lgkmcnt(0)
	v_mfma_f32_16x16x32_bf16 v[126:129], v[130:133], v[186:189], v[126:129]
	v_mfma_f32_16x16x32_bf16 v[122:125], v[152:155], v[186:189], v[122:125]
	v_mfma_f32_16x16x32_bf16 v[110:113], v[130:133], v[194:197], v[110:113]
	v_mfma_f32_16x16x32_bf16 v[106:109], v[152:155], v[194:197], v[106:109]
	v_mfma_f32_16x16x32_bf16 v[94:97], v[130:133], v[202:205], v[94:97]
	v_mfma_f32_16x16x32_bf16 v[90:93], v[152:155], v[202:205], v[90:93]
	v_mfma_f32_16x16x32_bf16 v[78:81], v[130:133], v[210:213], v[78:81]
	v_mfma_f32_16x16x32_bf16 v[74:77], v[152:155], v[210:213], v[74:77]
	v_mfma_f32_16x16x32_bf16 v[126:129], v[134:137], v[190:193], v[126:129]
	v_mfma_f32_16x16x32_bf16 v[122:125], v[156:159], v[190:193], v[122:125]
	v_mfma_f32_16x16x32_bf16 v[110:113], v[134:137], v[198:201], v[110:113]
	v_mfma_f32_16x16x32_bf16 v[106:109], v[156:159], v[198:201], v[106:109]
	v_mfma_f32_16x16x32_bf16 v[94:97], v[134:137], v[206:209], v[94:97]
	v_mfma_f32_16x16x32_bf16 v[90:93], v[156:159], v[206:209], v[90:93]
	v_mfma_f32_16x16x32_bf16 v[78:81], v[134:137], v[214:217], v[78:81]
	v_mfma_f32_16x16x32_bf16 v[74:77], v[156:159], v[214:217], v[74:77]
	s_setprio 0
	s_setprio 1
	v_mfma_f32_16x16x32_bf16 v[118:121], v[166:169], v[186:189], v[118:121]
	v_mfma_f32_16x16x32_bf16 v[114:117], v[174:177], v[186:189], v[114:117]
	v_mfma_f32_16x16x32_bf16 v[102:105], v[166:169], v[194:197], v[102:105]
	v_mfma_f32_16x16x32_bf16 v[98:101], v[174:177], v[194:197], v[98:101]
	v_mfma_f32_16x16x32_bf16 v[86:89], v[166:169], v[202:205], v[86:89]
	v_mfma_f32_16x16x32_bf16 v[82:85], v[174:177], v[202:205], v[82:85]
	v_mfma_f32_16x16x32_bf16 v[70:73], v[166:169], v[210:213], v[70:73]
	v_mfma_f32_16x16x32_bf16 v[66:69], v[174:177], v[210:213], v[66:69]
	v_mfma_f32_16x16x32_bf16 v[118:121], v[170:173], v[190:193], v[118:121]
	v_mfma_f32_16x16x32_bf16 v[114:117], v[182:185], v[190:193], v[114:117]
	v_mfma_f32_16x16x32_bf16 v[102:105], v[170:173], v[198:201], v[102:105]
	v_mfma_f32_16x16x32_bf16 v[98:101], v[182:185], v[198:201], v[98:101]
	v_mfma_f32_16x16x32_bf16 v[86:89], v[170:173], v[206:209], v[86:89]
	v_mfma_f32_16x16x32_bf16 v[82:85], v[182:185], v[206:209], v[82:85]
	v_mfma_f32_16x16x32_bf16 v[70:73], v[170:173], v[214:217], v[70:73]
	v_mfma_f32_16x16x32_bf16 v[66:69], v[182:185], v[214:217], v[66:69]
	s_setprio 0
	s_barrier
	s_add_i32 s90, s83, s15
	v_lshl_add_u64 v[178:179], s[60:61], 0, v[138:139]
	s_mov_b32 m0, s90
	ds_read_b128 v[186:189], v163 offset:16384
	ds_read_b128 v[190:193], v163 offset:17408
	ds_read_b128 v[194:197], v163 offset:18432
	ds_read_b128 v[198:201], v163 offset:19456
	ds_read_b128 v[202:205], v163 offset:20480
	ds_read_b128 v[206:209], v163 offset:21504
	ds_read_b128 v[210:213], v163 offset:22528
	ds_read_b128 v[214:217], v163 offset:23552
	global_load_lds_dwordx4 v[178:179], off
	s_add_i32 m0, s90, 0x2000
	s_add_u32 s90, s60, 0x80000
	v_lshl_add_u64 v[178:179], s[60:61], 0, v[140:141]
	s_addc_u32 s91, s61, 0
	s_add_i32 s92, s86, s15
	global_load_lds_dwordx4 v[178:179], off
	v_lshl_add_u64 v[178:179], s[90:91], 0, v[138:139]
	s_mov_b32 m0, s92
	s_nop 0
	global_load_lds_dwordx4 v[178:179], off
	v_lshl_add_u64 v[178:179], s[90:91], 0, v[140:141]
	s_add_i32 m0, s92, 0x2000
	s_nop 0
	global_load_lds_dwordx4 v[178:179], off
	v_lshl_add_u64 v[178:179], s[70:71], 0, v[138:139]
	s_mov_b32 m0, s72
	s_nop 0
	global_load_lds_dwordx4 v[178:179], off
	v_lshl_add_u64 v[178:179], s[70:71], 0, v[140:141]
	s_mov_b32 m0, s73
	s_nop 0
	global_load_lds_dwordx4 v[178:179], off
	s_waitcnt vmcnt(8)
	s_waitcnt lgkmcnt(0)
	s_barrier
; #define PG8_STAGE(bufoff, gbase, voff) do { _Pragma("unroll") for (int _i = 0; _i < 2; ++_i) \
;         __builtin_amdgcn_global_load_lds((const unsigned*)((const char*)(gbase) + (voff)[_i]), (PG8_LAS unsigned*)(lds + (bufoff) + ldsw + _i * 8192), 16, 0, 0); } while (0)
; #define PG8_LDA(dst, b, h) do { _Pragma("unroll") for (int m = 0; m < 4; ++m) _Pragma("unroll") for (int k = 0; k < 2; ++k) dst[m][k] = *(const PG8_LAS bf16x8*)(lds + PG8_SA(b, h) + aoff + m * 2048 + k * 1024); } while (0)
; #define PG8_LDB(dst, b, h) do { _Pragma("unroll") for (int n = 0; n < 2; ++n) _Pragma("unroll") for (int k = 0; k < 2; ++k) dst[n][k] = *(const PG8_LAS bf16x8*)(lds + PG8_SB(b, h) + boff + n * 2048 + k * 1024); } while (0)
; #define PG8_MMA(ai, bj, At, Bt) do { __builtin_amdgcn_s_setprio(1); _Pragma("unroll") for (int m = 0; m < 4; ++m) _Pragma("unroll") for (int n = 0; n < 2; ++n) _Pragma("unroll") for (int k = 0; k < 2; ++k) \
;         acc[ai][bj][m][n] = __builtin_amdgcn_mfma_f32_16x16x32_bf16(Bt[n][k], At[m][k], acc[ai][bj][m][n], 0, 0, 0); __builtin_amdgcn_s_setprio(0); } while (0)
; #define PG8_WAIT_V(n) asm volatile("s_waitcnt vmcnt(" #n ")" ::: "memory")
; #define PG8_WAIT_L(n) asm volatile("s_waitcnt lgkmcnt(" #n ")" ::: "memory")
; #define PG8_BAR __builtin_amdgcn_s_barrier()
; #define PG8_SCHED __builtin_amdgcn_sched_barrier(0)
; template <class Epi, class Sched, bool ALIGN_EPI = false, bool SP2 = false, bool RS = false, bool BPRE = false>
; __device__ __forceinline__ void gemm_phase(PG8_LAS unsigned char* lds, const Gemm g, const Sched& S, const Epi& E, const float* rs_ss = nullptr, PG8_LAS float* rs_tab = nullptr) {
;     ...
;             PG8_WAIT_V(8); PG8_WAIT_L(0); PG8_BAR; PG8_MMA(1, 0, At, B0); PG8_MMA(1, 1, At, B1); PG8_BAR; PG8_SCHED;
;             PG8_LDB(B0, 1, 0); PG8_LDB(B1, 1, 1); PG8_SCHED; PG8_LDA(At, 1, 0); PG8_STAGE(PG8_SA(0, 1), a2 + hstep, voffA);
;             PG8_WAIT_V(8); PG8_WAIT_L(0); PG8_BAR; PG8_MMA(0, 0, At, B0); PG8_MMA(0, 1, At, B1); PG8_BAR; PG8_SCHED;
	s_setprio 1
	s_waitcnt lgkmcnt(0)
	v_mfma_f32_16x16x32_bf16 v[62:65], v[130:133], v[186:189], v[62:65]
	v_mfma_f32_16x16x32_bf16 v[58:61], v[152:155], v[186:189], v[58:61]
	v_mfma_f32_16x16x32_bf16 v[46:49], v[130:133], v[194:197], v[46:49]
	v_mfma_f32_16x16x32_bf16 v[42:45], v[152:155], v[194:197], v[42:45]
	v_mfma_f32_16x16x32_bf16 v[30:33], v[130:133], v[202:205], v[30:33]
	v_mfma_f32_16x16x32_bf16 v[26:29], v[152:155], v[202:205], v[26:29]
	v_mfma_f32_16x16x32_bf16 v[14:17], v[130:133], v[210:213], v[14:17]
	v_mfma_f32_16x16x32_bf16 v[10:13], v[152:155], v[210:213], v[10:13]
	v_mfma_f32_16x16x32_bf16 v[62:65], v[134:137], v[190:193], v[62:65]
	v_mfma_f32_16x16x32_bf16 v[58:61], v[156:159], v[190:193], v[58:61]
	v_mfma_f32_16x16x32_bf16 v[46:49], v[134:137], v[198:201], v[46:49]
	v_mfma_f32_16x16x32_bf16 v[42:45], v[156:159], v[198:201], v[42:45]
	v_mfma_f32_16x16x32_bf16 v[30:33], v[134:137], v[206:209], v[30:33]
	v_mfma_f32_16x16x32_bf16 v[26:29], v[156:159], v[206:209], v[26:29]
	v_mfma_f32_16x16x32_bf16 v[14:17], v[134:137], v[214:217], v[14:17]
	v_mfma_f32_16x16x32_bf16 v[10:13], v[156:159], v[214:217], v[10:13]
	s_setprio 0
	s_setprio 1
	v_mfma_f32_16x16x32_bf16 v[54:57], v[166:169], v[186:189], v[54:57]
	v_mfma_f32_16x16x32_bf16 v[50:53], v[174:177], v[186:189], v[50:53]
	v_mfma_f32_16x16x32_bf16 v[38:41], v[166:169], v[194:197], v[38:41]
	v_mfma_f32_16x16x32_bf16 v[34:37], v[174:177], v[194:197], v[34:37]
	v_mfma_f32_16x16x32_bf16 v[22:25], v[166:169], v[202:205], v[22:25]
	v_mfma_f32_16x16x32_bf16 v[18:21], v[174:177], v[202:205], v[18:21]
	v_mfma_f32_16x16x32_bf16 v[6:9], v[166:169], v[210:213], v[6:9]
	v_mfma_f32_16x16x32_bf16 v[2:5], v[174:177], v[210:213], v[2:5]
	v_mfma_f32_16x16x32_bf16 v[54:57], v[170:173], v[190:193], v[54:57]
	v_mfma_f32_16x16x32_bf16 v[50:53], v[182:185], v[190:193], v[50:53]
	v_mfma_f32_16x16x32_bf16 v[38:41], v[170:173], v[198:201], v[38:41]
	v_mfma_f32_16x16x32_bf16 v[34:37], v[182:185], v[198:201], v[34:37]
	v_mfma_f32_16x16x32_bf16 v[22:25], v[170:173], v[206:209], v[22:25]
	v_mfma_f32_16x16x32_bf16 v[18:21], v[182:185], v[206:209], v[18:21]
	v_mfma_f32_16x16x32_bf16 v[6:9], v[170:173], v[214:217], v[6:9]
	v_mfma_f32_16x16x32_bf16 v[2:5], v[182:185], v[214:217], v[2:5]
	s_setprio 0
	s_barrier
	s_add_i32 s90, 0, 0x18000
	v_add_u32_e32 v143, s90, v160
	s_add_i32 s91, 0, 0x1c000
	ds_read_b128 v[130:133], v143
	ds_read_b128 v[134:137], v143 offset:1024
	ds_read_b128 v[152:155], v143 offset:2048
	ds_read_b128 v[156:159], v143 offset:3072
	v_add_u32_e32 v143, s91, v160
	ds_read_b128 v[166:169], v143
	ds_read_b128 v[170:173], v143 offset:1024
	ds_read_b128 v[174:177], v143 offset:2048
	ds_read_b128 v[182:185], v143 offset:3072
	s_add_u32 s70, s70, 0x80000
	s_addc_u32 s71, s71, 0
	s_mov_b32 m0, s74
	v_lshl_add_u64 v[178:179], s[70:71], 0, v[138:139]
	ds_read_b128 v[186:189], v163 offset:32768
	ds_read_b128 v[190:193], v163 offset:33792
	ds_read_b128 v[194:197], v163 offset:34816
	ds_read_b128 v[198:201], v163 offset:35840
	ds_read_b128 v[202:205], v163 offset:36864
	ds_read_b128 v[206:209], v163 offset:37888
	ds_read_b128 v[210:213], v163 offset:38912
	ds_read_b128 v[214:217], v163 offset:39936
	global_load_lds_dwordx4 v[178:179], off
	v_lshl_add_u64 v[178:179], s[70:71], 0, v[140:141]
	s_mov_b32 m0, s75
	s_nop 0
	global_load_lds_dwordx4 v[178:179], off
	s_waitcnt vmcnt(8)
	s_waitcnt lgkmcnt(0)
	s_barrier
	s_setprio 1
	s_waitcnt lgkmcnt(0)
	v_mfma_f32_16x16x32_bf16 v[126:129], v[130:133], v[186:189], v[126:129]
	v_mfma_f32_16x16x32_bf16 v[122:125], v[152:155], v[186:189], v[122:125]
	v_mfma_f32_16x16x32_bf16 v[110:113], v[130:133], v[194:197], v[110:113]
	v_mfma_f32_16x16x32_bf16 v[106:109], v[152:155], v[194:197], v[106:109]
	v_mfma_f32_16x16x32_bf16 v[94:97], v[130:133], v[202:205], v[94:97]
	v_mfma_f32_16x16x32_bf16 v[90:93], v[152:155], v[202:205], v[90:93]
	v_mfma_f32_16x16x32_bf16 v[78:81], v[130:133], v[210:213], v[78:81]
	v_mfma_f32_16x16x32_bf16 v[74:77], v[152:155], v[210:213], v[74:77]
	v_mfma_f32_16x16x32_bf16 v[126:129], v[134:137], v[190:193], v[126:129]
	v_mfma_f32_16x16x32_bf16 v[122:125], v[156:159], v[190:193], v[122:125]
	v_mfma_f32_16x16x32_bf16 v[110:113], v[134:137], v[198:201], v[110:113]
	v_mfma_f32_16x16x32_bf16 v[106:109], v[156:159], v[198:201], v[106:109]
	v_mfma_f32_16x16x32_bf16 v[94:97], v[134:137], v[206:209], v[94:97]
	v_mfma_f32_16x16x32_bf16 v[90:93], v[156:159], v[206:209], v[90:93]
	v_mfma_f32_16x16x32_bf16 v[78:81], v[134:137], v[214:217], v[78:81]
	v_mfma_f32_16x16x32_bf16 v[74:77], v[156:159], v[214:217], v[74:77]
	s_setprio 0
	s_setprio 1
	v_mfma_f32_16x16x32_bf16 v[118:121], v[166:169], v[186:189], v[118:121]
	v_mfma_f32_16x16x32_bf16 v[114:117], v[174:177], v[186:189], v[114:117]
	v_mfma_f32_16x16x32_bf16 v[102:105], v[166:169], v[194:197], v[102:105]
	v_mfma_f32_16x16x32_bf16 v[98:101], v[174:177], v[194:197], v[98:101]
	v_mfma_f32_16x16x32_bf16 v[86:89], v[166:169], v[202:205], v[86:89]
	v_mfma_f32_16x16x32_bf16 v[82:85], v[174:177], v[202:205], v[82:85]
	v_mfma_f32_16x16x32_bf16 v[70:73], v[166:169], v[210:213], v[70:73]
	v_mfma_f32_16x16x32_bf16 v[66:69], v[174:177], v[210:213], v[66:69]
	v_mfma_f32_16x16x32_bf16 v[118:121], v[170:173], v[190:193], v[118:121]
	v_mfma_f32_16x16x32_bf16 v[114:117], v[182:185], v[190:193], v[114:117]
	v_mfma_f32_16x16x32_bf16 v[102:105], v[170:173], v[198:201], v[102:105]
	v_mfma_f32_16x16x32_bf16 v[98:101], v[182:185], v[198:201], v[98:101]
	v_mfma_f32_16x16x32_bf16 v[86:89], v[170:173], v[206:209], v[86:89]
	v_mfma_f32_16x16x32_bf16 v[82:85], v[182:185], v[206:209], v[82:85]
	v_mfma_f32_16x16x32_bf16 v[70:73], v[170:173], v[214:217], v[70:73]
	v_mfma_f32_16x16x32_bf16 v[66:69], v[182:185], v[214:217], v[66:69]
	s_setprio 0
	s_barrier
; #define PG8_STAGE(bufoff, gbase, voff) do { _Pragma("unroll") for (int _i = 0; _i < 2; ++_i) \
;         __builtin_amdgcn_global_load_lds((const unsigned*)((const char*)(gbase) + (voff)[_i]), (PG8_LAS unsigned*)(lds + (bufoff) + ldsw + _i * 8192), 16, 0, 0); } while (0)
; #define PG8_LDA(dst, b, h) do { _Pragma("unroll") for (int m = 0; m < 4; ++m) _Pragma("unroll") for (int k = 0; k < 2; ++k) dst[m][k] = *(const PG8_LAS bf16x8*)(lds + PG8_SA(b, h) + aoff + m * 2048 + k * 1024); } while (0)
; #define PG8_WAIT_V(n) asm volatile("s_waitcnt vmcnt(" #n ")" ::: "memory")
; #define PG8_WAIT_L(n) asm volatile("s_waitcnt lgkmcnt(" #n ")" ::: "memory")
; template <class Epi, class Sched, bool ALIGN_EPI = false, bool SP2 = false, bool RS = false, bool BPRE = false>
; __device__ __forceinline__ void gemm_phase(PG8_LAS unsigned char* lds, const Gemm g, const Sched& S, const Epi& E, const float* rs_ss = nullptr, PG8_LAS float* rs_tab = nullptr) {
;     ...
;             const char* a1 = cA + (size_t)(t + 1) * kstep;
;             const char* a2 = last ? nA : cA + (size_t)(t + 2) * kstep; const char* b2 = last ? nB : cB + (size_t)(t + 2) * kstep;
;             const char* a3 = a2 + kstep; const char* b3 = b2 + kstep;
;             if (last && has_next) S.a_ready(nxt);
;             if constexpr (SP2) {
;             PG8_LDB(B0, 0, 0); PG8_LDB(B1, 0, 1); PG8_SCHED; PG8_LDA(At, 0, 0); PG8_STAGE(PG8_SA(1, 1), a1 + hstep, voffA);
;             PG8_WAIT_V(8); PG8_WAIT_L(0); PG8_BAR; PG8_MMA(0, 0, At, B0); PG8_MMA(0, 1, At, B1); PG8_BAR; PG8_SCHED;
;             PG8_LDA(At, 0, 1); PG8_STAGE(PG8_SB(0, 0), b2, voffB); PG8_STAGE(PG8_SB(0, 1), b2 + hstep, voffB); PG8_STAGE(PG8_SA(0, 0), a2, voffA);
;             PG8_WAIT_V(8); PG8_WAIT_L(0); PG8_BAR; PG8_MMA(1, 0, At, B0); PG8_MMA(1, 1, At, B1); PG8_BAR; PG8_SCHED;
;             PG8_LDB(B0, 1, 0); PG8_LDB(B1, 1, 1); PG8_SCHED; PG8_LDA(At, 1, 0); PG8_STAGE(PG8_SA(0, 1), a2 + hstep, voffA);
;             PG8_WAIT_V(8); PG8_WAIT_L(0); PG8_BAR; PG8_MMA(0, 0, At, B0); PG8_MMA(0, 1, At, B1); PG8_BAR; PG8_SCHED;
;             PG8_LDA(At, 1, 1); PG8_STAGE(PG8_SB(1, 0), b3, voffB); PG8_STAGE(PG8_SB(1, 1), b3 + hstep, voffB); PG8_STAGE(PG8_SA(1, 0), a3, voffA);
;             PG8_WAIT_V(8); PG8_WAIT_L(0); PG8_BAR; PG8_MMA(1, 0, At, B0); PG8_MMA(1, 1, At, B1); PG8_BAR; PG8_SCHED;
;     ...
;         if constexpr (ALIGN_EPI) { if (wr == 0) PG8_BAR; }
	s_add_u32 s70, s60, 0x4000
	s_addc_u32 s71, s61, 0
	s_add_i32 s90, s90, s15
	v_lshl_add_u64 v[178:179], s[70:71], 0, v[138:139]
	s_mov_b32 m0, s90
	ds_read_b128 v[186:189], v163 offset:49152
	ds_read_b128 v[190:193], v163 offset:50176
	ds_read_b128 v[194:197], v163 offset:51200
	ds_read_b128 v[198:201], v163 offset:52224
	ds_read_b128 v[202:205], v163 offset:53248
	ds_read_b128 v[206:209], v163 offset:54272
	ds_read_b128 v[210:213], v163 offset:55296
	ds_read_b128 v[214:217], v163 offset:56320
	global_load_lds_dwordx4 v[178:179], off
	s_add_i32 m0, s90, 0x2000
	s_add_u32 s60, s60, 0x84000
	v_lshl_add_u64 v[178:179], s[70:71], 0, v[140:141]
	s_addc_u32 s61, s61, 0
	s_add_i32 s70, s91, s15
	global_load_lds_dwordx4 v[178:179], off
	v_lshl_add_u64 v[178:179], s[60:61], 0, v[138:139]
	s_mov_b32 m0, s70
	s_nop 0
	global_load_lds_dwordx4 v[178:179], off
	v_lshl_add_u64 v[178:179], s[60:61], 0, v[140:141]
	s_add_i32 m0, s70, 0x2000
	s_nop 0
	global_load_lds_dwordx4 v[178:179], off
	v_lshl_add_u64 v[178:179], s[58:59], 0, v[138:139]
	s_mov_b32 m0, s79
	s_nop 0
	global_load_lds_dwordx4 v[178:179], off
	v_lshl_add_u64 v[178:179], s[58:59], 0, v[140:141]
	s_mov_b32 m0, s80
	s_nop 0
	global_load_lds_dwordx4 v[178:179], off
	s_waitcnt vmcnt(8)
	s_waitcnt lgkmcnt(0)
	s_barrier
	s_setprio 1
	s_waitcnt lgkmcnt(0)
	v_mfma_f32_16x16x32_bf16 v[62:65], v[130:133], v[186:189], v[62:65]
	v_mfma_f32_16x16x32_bf16 v[58:61], v[152:155], v[186:189], v[58:61]
	v_mfma_f32_16x16x32_bf16 v[46:49], v[130:133], v[194:197], v[46:49]
	v_mfma_f32_16x16x32_bf16 v[42:45], v[152:155], v[194:197], v[42:45]
	v_mfma_f32_16x16x32_bf16 v[30:33], v[130:133], v[202:205], v[30:33]
	v_mfma_f32_16x16x32_bf16 v[26:29], v[152:155], v[202:205], v[26:29]
	v_mfma_f32_16x16x32_bf16 v[14:17], v[130:133], v[210:213], v[14:17]
	v_mfma_f32_16x16x32_bf16 v[10:13], v[152:155], v[210:213], v[10:13]
	v_mfma_f32_16x16x32_bf16 v[62:65], v[134:137], v[190:193], v[62:65]
	v_mfma_f32_16x16x32_bf16 v[58:61], v[156:159], v[190:193], v[58:61]
	v_mfma_f32_16x16x32_bf16 v[46:49], v[134:137], v[198:201], v[46:49]
	v_mfma_f32_16x16x32_bf16 v[42:45], v[156:159], v[198:201], v[42:45]
	v_mfma_f32_16x16x32_bf16 v[30:33], v[134:137], v[206:209], v[30:33]
	v_mfma_f32_16x16x32_bf16 v[26:29], v[156:159], v[206:209], v[26:29]
	v_mfma_f32_16x16x32_bf16 v[14:17], v[134:137], v[214:217], v[14:17]
	v_mfma_f32_16x16x32_bf16 v[10:13], v[156:159], v[214:217], v[10:13]
	s_setprio 0
	s_setprio 1
	v_mfma_f32_16x16x32_bf16 v[54:57], v[166:169], v[186:189], v[54:57]
	v_mfma_f32_16x16x32_bf16 v[50:53], v[174:177], v[186:189], v[50:53]
	v_mfma_f32_16x16x32_bf16 v[38:41], v[166:169], v[194:197], v[38:41]
	v_mfma_f32_16x16x32_bf16 v[34:37], v[174:177], v[194:197], v[34:37]
	v_mfma_f32_16x16x32_bf16 v[22:25], v[166:169], v[202:205], v[22:25]
	v_mfma_f32_16x16x32_bf16 v[18:21], v[174:177], v[202:205], v[18:21]
	v_mfma_f32_16x16x32_bf16 v[6:9], v[166:169], v[210:213], v[6:9]
	v_mfma_f32_16x16x32_bf16 v[2:5], v[174:177], v[210:213], v[2:5]
	v_mfma_f32_16x16x32_bf16 v[54:57], v[170:173], v[190:193], v[54:57]
	v_mfma_f32_16x16x32_bf16 v[50:53], v[182:185], v[190:193], v[50:53]
	v_mfma_f32_16x16x32_bf16 v[38:41], v[170:173], v[198:201], v[38:41]
	v_mfma_f32_16x16x32_bf16 v[34:37], v[182:185], v[198:201], v[34:37]
	v_mfma_f32_16x16x32_bf16 v[22:25], v[170:173], v[206:209], v[22:25]
	v_mfma_f32_16x16x32_bf16 v[18:21], v[182:185], v[206:209], v[18:21]
	v_mfma_f32_16x16x32_bf16 v[6:9], v[170:173], v[214:217], v[6:9]
	v_mfma_f32_16x16x32_bf16 v[2:5], v[182:185], v[214:217], v[2:5]
	s_setprio 0
	s_barrier
	s_add_i32 s89, s89, 2
	s_add_u32 s56, s56, 0x8000
	s_addc_u32 s57, s57, 0
	s_add_u32 s87, s87, 0x8000
	s_addc_u32 s88, s88, 0
	s_cmp_gt_u32 s89, 27
	s_cbranch_scc0 .LBB0_196
	ds_read_b128 v[130:133], v161
	ds_read_b128 v[134:137], v161 offset:1024
	ds_read_b128 v[152:155], v161 offset:2048
	ds_read_b128 v[156:159], v161 offset:3072
	ds_read_b128 v[166:169], v162
	ds_read_b128 v[170:173], v162 offset:1024
	ds_read_b128 v[174:177], v162 offset:2048
	ds_read_b128 v[182:185], v162 offset:3072
	s_add_u32 s58, s56, 0xfff84000
	s_addc_u32 s59, s57, -1
	s_cmp_eq_u32 s89, 28
	s_cselect_b32 s70, s19, s58
	s_cselect_b32 s71, s5, s59
	s_cselect_b32 s60, s47, s87
	s_cselect_b32 s61, s17, s88
	s_add_u32 s58, s70, 0x4000
	s_addc_u32 s59, s71, 0
	v_lshl_add_u64 v[178:179], s[56:57], 0, v[138:139]
	s_add_i32 m0, s72, 0xc000
	ds_read_b128 v[186:189], v163
	ds_read_b128 v[190:193], v163 offset:1024
	ds_read_b128 v[194:197], v163 offset:2048
	ds_read_b128 v[198:201], v163 offset:3072
	ds_read_b128 v[202:205], v163 offset:4096
	ds_read_b128 v[206:209], v163 offset:5120
	ds_read_b128 v[210:213], v163 offset:6144
	ds_read_b128 v[214:217], v163 offset:7168
	global_load_lds_dwordx4 v[178:179], off
	v_lshl_add_u64 v[178:179], s[56:57], 0, v[146:147]
	s_add_i32 m0, s72, 0xe000
	s_nop 0
	global_load_lds_dwordx4 v[178:179], off
	s_waitcnt vmcnt(8)
	s_waitcnt lgkmcnt(0)
	s_barrier
; #define PG8_STAGE(bufoff, gbase, voff) do { _Pragma("unroll") for (int _i = 0; _i < 2; ++_i) \
;         __builtin_amdgcn_global_load_lds((const unsigned*)((const char*)(gbase) + (voff)[_i]), (PG8_LAS unsigned*)(lds + (bufoff) + ldsw + _i * 8192), 16, 0, 0); } while (0)
; #define PG8_LDA(dst, b, h) do { _Pragma("unroll") for (int m = 0; m < 4; ++m) _Pragma("unroll") for (int k = 0; k < 2; ++k) dst[m][k] = *(const PG8_LAS bf16x8*)(lds + PG8_SA(b, h) + aoff + m * 2048 + k * 1024); } while (0)
; #define PG8_LDB(dst, b, h) do { _Pragma("unroll") for (int n = 0; n < 2; ++n) _Pragma("unroll") for (int k = 0; k < 2; ++k) dst[n][k] = *(const PG8_LAS bf16x8*)(lds + PG8_SB(b, h) + boff + n * 2048 + k * 1024); } while (0)
; #define PG8_MMA(ai, bj, At, Bt) do { __builtin_amdgcn_s_setprio(1); _Pragma("unroll") for (int m = 0; m < 4; ++m) _Pragma("unroll") for (int n = 0; n < 2; ++n) _Pragma("unroll") for (int k = 0; k < 2; ++k) \
;         acc[ai][bj][m][n] = __builtin_amdgcn_mfma_f32_16x16x32_bf16(Bt[n][k], At[m][k], acc[ai][bj][m][n], 0, 0, 0); __builtin_amdgcn_s_setprio(0); } while (0)
; #define PG8_WAIT_V(n) asm volatile("s_waitcnt vmcnt(" #n ")" ::: "memory")
; #define PG8_WAIT_L(n) asm volatile("s_waitcnt lgkmcnt(" #n ")" ::: "memory")
; #define PG8_BAR __builtin_amdgcn_s_barrier()
; #define PG8_SCHED __builtin_amdgcn_sched_barrier(0)
; template <class Epi, class Sched, bool ALIGN_EPI = false, bool SP2 = false, bool RS = false, bool BPRE = false>
; __device__ __forceinline__ void gemm_phase(PG8_LAS unsigned char* lds, const Gemm g, const Sched& S, const Epi& E, const float* rs_ss = nullptr, PG8_LAS float* rs_tab = nullptr) {
;     ...
;             PG8_LDB(B0, 0, 0); PG8_LDB(B1, 0, 1); PG8_SCHED; PG8_LDA(At, 0, 0); PG8_STAGE(PG8_SA(1, 1), a1 + hstep, voffA);
;             PG8_WAIT_V(8); PG8_WAIT_L(0); PG8_BAR; PG8_MMA(0, 0, At, B0); PG8_MMA(0, 1, At, B1); PG8_BAR; PG8_SCHED;
;             PG8_LDA(At, 0, 1); PG8_STAGE(PG8_SB(0, 0), b2, voffB); PG8_STAGE(PG8_SB(0, 1), b2 + hstep, voffB); PG8_STAGE(PG8_SA(0, 0), a2, voffA);
;             PG8_WAIT_V(8); PG8_WAIT_L(0); PG8_BAR; PG8_MMA(1, 0, At, B0); PG8_MMA(1, 1, At, B1); PG8_BAR; PG8_SCHED;
	s_setprio 1
	s_waitcnt lgkmcnt(0)
	v_mfma_f32_16x16x32_bf16 v[126:129], v[130:133], v[186:189], v[126:129]
	v_mfma_f32_16x16x32_bf16 v[122:125], v[152:155], v[186:189], v[122:125]
	v_mfma_f32_16x16x32_bf16 v[110:113], v[130:133], v[194:197], v[110:113]
	v_mfma_f32_16x16x32_bf16 v[106:109], v[152:155], v[194:197], v[106:109]
	v_mfma_f32_16x16x32_bf16 v[94:97], v[130:133], v[202:205], v[94:97]
	v_mfma_f32_16x16x32_bf16 v[90:93], v[152:155], v[202:205], v[90:93]
	v_mfma_f32_16x16x32_bf16 v[78:81], v[130:133], v[210:213], v[78:81]
	v_mfma_f32_16x16x32_bf16 v[74:77], v[152:155], v[210:213], v[74:77]
	v_mfma_f32_16x16x32_bf16 v[126:129], v[134:137], v[190:193], v[126:129]
	v_mfma_f32_16x16x32_bf16 v[122:125], v[156:159], v[190:193], v[122:125]
	v_mfma_f32_16x16x32_bf16 v[110:113], v[134:137], v[198:201], v[110:113]
	v_mfma_f32_16x16x32_bf16 v[106:109], v[156:159], v[198:201], v[106:109]
	v_mfma_f32_16x16x32_bf16 v[94:97], v[134:137], v[206:209], v[94:97]
	v_mfma_f32_16x16x32_bf16 v[90:93], v[156:159], v[206:209], v[90:93]
	v_mfma_f32_16x16x32_bf16 v[78:81], v[134:137], v[214:217], v[78:81]
	v_mfma_f32_16x16x32_bf16 v[74:77], v[156:159], v[214:217], v[74:77]
	s_setprio 0
	s_setprio 1
	v_mfma_f32_16x16x32_bf16 v[118:121], v[166:169], v[186:189], v[118:121]
	v_mfma_f32_16x16x32_bf16 v[114:117], v[174:177], v[186:189], v[114:117]
	v_mfma_f32_16x16x32_bf16 v[102:105], v[166:169], v[194:197], v[102:105]
	v_mfma_f32_16x16x32_bf16 v[98:101], v[174:177], v[194:197], v[98:101]
	v_mfma_f32_16x16x32_bf16 v[86:89], v[166:169], v[202:205], v[86:89]
	v_mfma_f32_16x16x32_bf16 v[82:85], v[174:177], v[202:205], v[82:85]
	v_mfma_f32_16x16x32_bf16 v[70:73], v[166:169], v[210:213], v[70:73]
	v_mfma_f32_16x16x32_bf16 v[66:69], v[174:177], v[210:213], v[66:69]
	v_mfma_f32_16x16x32_bf16 v[118:121], v[170:173], v[190:193], v[118:121]
	v_mfma_f32_16x16x32_bf16 v[114:117], v[182:185], v[190:193], v[114:117]
	v_mfma_f32_16x16x32_bf16 v[102:105], v[170:173], v[198:201], v[102:105]
	v_mfma_f32_16x16x32_bf16 v[98:101], v[182:185], v[198:201], v[98:101]
	v_mfma_f32_16x16x32_bf16 v[86:89], v[170:173], v[206:209], v[86:89]
	v_mfma_f32_16x16x32_bf16 v[82:85], v[182:185], v[206:209], v[82:85]
	v_mfma_f32_16x16x32_bf16 v[70:73], v[170:173], v[214:217], v[70:73]
	v_mfma_f32_16x16x32_bf16 v[66:69], v[182:185], v[214:217], v[66:69]
	s_setprio 0
	s_barrier
	s_add_i32 s90, s83, s15
	v_lshl_add_u64 v[178:179], s[60:61], 0, v[138:139]
	s_mov_b32 m0, s90
	ds_read_b128 v[186:189], v163 offset:16384
	ds_read_b128 v[190:193], v163 offset:17408
	ds_read_b128 v[194:197], v163 offset:18432
	ds_read_b128 v[198:201], v163 offset:19456
	ds_read_b128 v[202:205], v163 offset:20480
	ds_read_b128 v[206:209], v163 offset:21504
	ds_read_b128 v[210:213], v163 offset:22528
	ds_read_b128 v[214:217], v163 offset:23552
	global_load_lds_dwordx4 v[178:179], off
	s_add_i32 m0, s90, 0x2000
	s_add_u32 s90, s60, 0x80000
	v_lshl_add_u64 v[178:179], s[60:61], 0, v[140:141]
	s_addc_u32 s91, s61, 0
	s_add_i32 s92, s86, s15
	global_load_lds_dwordx4 v[178:179], off
	v_lshl_add_u64 v[178:179], s[90:91], 0, v[138:139]
	s_mov_b32 m0, s92
	s_nop 0
	global_load_lds_dwordx4 v[178:179], off
	v_lshl_add_u64 v[178:179], s[90:91], 0, v[140:141]
	s_add_i32 m0, s92, 0x2000
	s_nop 0
	global_load_lds_dwordx4 v[178:179], off
	v_lshl_add_u64 v[178:179], s[70:71], 0, v[138:139]
	s_mov_b32 m0, s72
	s_nop 0
	global_load_lds_dwordx4 v[178:179], off
	v_lshl_add_u64 v[178:179], s[70:71], 0, v[140:141]
	s_mov_b32 m0, s73
	s_nop 0
	global_load_lds_dwordx4 v[178:179], off
	s_waitcnt vmcnt(8)
	s_waitcnt lgkmcnt(0)
	s_barrier
	s_setprio 1
	s_waitcnt lgkmcnt(0)
	v_mfma_f32_16x16x32_bf16 v[62:65], v[130:133], v[186:189], v[62:65]
	v_mfma_f32_16x16x32_bf16 v[58:61], v[152:155], v[186:189], v[58:61]
	v_mfma_f32_16x16x32_bf16 v[46:49], v[130:133], v[194:197], v[46:49]
	v_mfma_f32_16x16x32_bf16 v[42:45], v[152:155], v[194:197], v[42:45]
	v_mfma_f32_16x16x32_bf16 v[30:33], v[130:133], v[202:205], v[30:33]
	v_mfma_f32_16x16x32_bf16 v[26:29], v[152:155], v[202:205], v[26:29]
	v_mfma_f32_16x16x32_bf16 v[14:17], v[130:133], v[210:213], v[14:17]
	v_mfma_f32_16x16x32_bf16 v[10:13], v[152:155], v[210:213], v[10:13]
	v_mfma_f32_16x16x32_bf16 v[62:65], v[134:137], v[190:193], v[62:65]
	v_mfma_f32_16x16x32_bf16 v[58:61], v[156:159], v[190:193], v[58:61]
	v_mfma_f32_16x16x32_bf16 v[46:49], v[134:137], v[198:201], v[46:49]
	v_mfma_f32_16x16x32_bf16 v[42:45], v[156:159], v[198:201], v[42:45]
	v_mfma_f32_16x16x32_bf16 v[30:33], v[134:137], v[206:209], v[30:33]
	v_mfma_f32_16x16x32_bf16 v[26:29], v[156:159], v[206:209], v[26:29]
	v_mfma_f32_16x16x32_bf16 v[14:17], v[134:137], v[214:217], v[14:17]
	v_mfma_f32_16x16x32_bf16 v[10:13], v[156:159], v[214:217], v[10:13]
	s_setprio 0
	s_setprio 1
	v_mfma_f32_16x16x32_bf16 v[54:57], v[166:169], v[186:189], v[54:57]
	v_mfma_f32_16x16x32_bf16 v[50:53], v[174:177], v[186:189], v[50:53]
	v_mfma_f32_16x16x32_bf16 v[38:41], v[166:169], v[194:197], v[38:41]
	v_mfma_f32_16x16x32_bf16 v[34:37], v[174:177], v[194:197], v[34:37]
	v_mfma_f32_16x16x32_bf16 v[22:25], v[166:169], v[202:205], v[22:25]
	v_mfma_f32_16x16x32_bf16 v[18:21], v[174:177], v[202:205], v[18:21]
	v_mfma_f32_16x16x32_bf16 v[6:9], v[166:169], v[210:213], v[6:9]
	v_mfma_f32_16x16x32_bf16 v[2:5], v[174:177], v[210:213], v[2:5]
	v_mfma_f32_16x16x32_bf16 v[54:57], v[170:173], v[190:193], v[54:57]
	v_mfma_f32_16x16x32_bf16 v[50:53], v[182:185], v[190:193], v[50:53]
	v_mfma_f32_16x16x32_bf16 v[38:41], v[170:173], v[198:201], v[38:41]
	v_mfma_f32_16x16x32_bf16 v[34:37], v[182:185], v[198:201], v[34:37]
	v_mfma_f32_16x16x32_bf16 v[22:25], v[170:173], v[206:209], v[22:25]
	v_mfma_f32_16x16x32_bf16 v[18:21], v[182:185], v[206:209], v[18:21]
	v_mfma_f32_16x16x32_bf16 v[6:9], v[170:173], v[214:217], v[6:9]
	v_mfma_f32_16x16x32_bf16 v[2:5], v[182:185], v[214:217], v[2:5]
	s_setprio 0
	s_barrier
; #define PG8_STAGE(bufoff, gbase, voff) do { _Pragma("unroll") for (int _i = 0; _i < 2; ++_i) \
;         __builtin_amdgcn_global_load_lds((const unsigned*)((const char*)(gbase) + (voff)[_i]), (PG8_LAS unsigned*)(lds + (bufoff) + ldsw + _i * 8192), 16, 0, 0); } while (0)
; #define PG8_WAIT_V(n) asm volatile("s_waitcnt vmcnt(" #n ")" ::: "memory")
; #define PG8_WAIT_L(n) asm volatile("s_waitcnt lgkmcnt(" #n ")" ::: "memory")
; #define PG8_BAR __builtin_amdgcn_s_barrier()
; template <class Epi, class Sched, bool ALIGN_EPI = false, bool SP2 = false, bool RS = false, bool BPRE = false>
; __device__ __forceinline__ void gemm_phase(PG8_LAS unsigned char* lds, const Gemm g, const Sched& S, const Epi& E, const float* rs_ss = nullptr, PG8_LAS float* rs_tab = nullptr) {
;     ...
;             PG8_LDB(B0, 1, 0); PG8_LDB(B1, 1, 1); PG8_SCHED; PG8_LDA(At, 1, 0); PG8_STAGE(PG8_SA(0, 1), a2 + hstep, voffA);
;             PG8_WAIT_V(8); PG8_WAIT_L(0); PG8_BAR; PG8_MMA(0, 0, At, B0); PG8_MMA(0, 1, At, B1); PG8_BAR; PG8_SCHED;
;             PG8_LDA(At, 1, 1); PG8_STAGE(PG8_SB(1, 0), b3, voffB); PG8_STAGE(PG8_SB(1, 1), b3 + hstep, voffB); PG8_STAGE(PG8_SA(1, 0), a3, voffA);
;             PG8_WAIT_V(8); PG8_WAIT_L(0); PG8_BAR; PG8_MMA(1, 0, At, B0); PG8_MMA(1, 1, At, B1); PG8_BAR; PG8_SCHED;
;     __device__ __forceinline__ void operator()(const f32x4 (&acc)[2][2][4][2], const pg8::Unit& u, int wr, int wc, int fr, int fq, const LAS float* tab) const {
;     ...
;         if (mode == 0) { const int seg = pn >> 2; kind = (seg == 1 || seg == 4 || seg == 6) ? 1 : (seg == 5 ? 2 : (seg == 3 ? 3 : 0)); }
;         else if (mode == 1) { ldc = 256; if (pm >= 8) { pm -= 8; } else { pm -= 4; pn -= 8; base = O2; } base += (size_t)(pm * 4 + pn) * 65536; pm = 0; pn = 0; }
;         else { ldc = DMODEL; kind = 4; }
;         int col0 = pn * 256 + wc * 32 + 8 * fq; const int row0 = pm * 256 + wr * 64 + fr;
;         if (mode == 0) { ldc = 256; base = O + (size_t)pn * NTOK * 256; col0 = wc * 32 + 8 * fq; }
; #pragma unroll
;         for (int ai = 0; ai < 2; ++ai)
; #pragma unroll
;             for (int m = 0; m < 4; ++m) {
;                 const int row = row0 + ai * 128 + m * 16;
;                 bf16_t* rowp = (mode == 0) ? base + (size_t)(row >> 4) * 4096 + (size_t)(wc * 512 + (row & 15) * 32 + 8 * fq) : base + (size_t)row * ldc + col0;
;                 const int bjstep = (mode == 0) ? 4 * 512 : 128;
	s_add_i32 s90, 0, 0x18000
	v_add_u32_e32 v143, s90, v160
	s_add_i32 s91, 0, 0x1c000
	ds_read_b128 v[130:133], v143
	ds_read_b128 v[134:137], v143 offset:1024
	ds_read_b128 v[152:155], v143 offset:2048
	ds_read_b128 v[156:159], v143 offset:3072
	v_add_u32_e32 v143, s91, v160
	ds_read_b128 v[166:169], v143
	ds_read_b128 v[170:173], v143 offset:1024
	ds_read_b128 v[174:177], v143 offset:2048
	ds_read_b128 v[182:185], v143 offset:3072
	s_add_u32 s70, s70, 0x80000
	s_addc_u32 s71, s71, 0
	s_mov_b32 m0, s74
	v_lshl_add_u64 v[178:179], s[70:71], 0, v[138:139]
	ds_read_b128 v[186:189], v163 offset:32768
	ds_read_b128 v[190:193], v163 offset:33792
	ds_read_b128 v[194:197], v163 offset:34816
	ds_read_b128 v[198:201], v163 offset:35840
	ds_read_b128 v[202:205], v163 offset:36864
	ds_read_b128 v[206:209], v163 offset:37888
	ds_read_b128 v[210:213], v163 offset:38912
	ds_read_b128 v[214:217], v163 offset:39936
	global_load_lds_dwordx4 v[178:179], off
	v_lshl_add_u64 v[178:179], s[70:71], 0, v[140:141]
	s_mov_b32 m0, s75
	s_nop 0
	global_load_lds_dwordx4 v[178:179], off
	s_waitcnt vmcnt(8)
	s_waitcnt lgkmcnt(0)
	s_barrier
	s_setprio 1
	s_waitcnt lgkmcnt(0)
	v_mfma_f32_16x16x32_bf16 v[126:129], v[130:133], v[186:189], v[126:129]
	v_and_b32_e32 v218, 15, v164
	v_bfe_u32 v219, v164, 4, 2
	v_mfma_f32_16x16x32_bf16 v[122:125], v[152:155], v[186:189], v[122:125]
	v_lshlrev_b32_e32 v218, 6, v218
	v_lshl_or_b32 v218, v219, 4, v218
	v_mfma_f32_16x16x32_bf16 v[110:113], v[130:133], v[194:197], v[110:113]
	s_and_b32 s93, s33, 3
	v_mfma_f32_16x16x32_bf16 v[106:109], v[152:155], v[194:197], v[106:109]
	s_lshl_b32 s94, s93, 10
	v_mfma_f32_16x16x32_bf16 v[94:97], v[130:133], v[202:205], v[94:97]
	v_or_b32_e32 v218, s94, v218
	v_mfma_f32_16x16x32_bf16 v[90:93], v[152:155], v[202:205], v[90:93]
	v_and_b32_e32 v219, 15, v164
	v_mfma_f32_16x16x32_bf16 v[78:81], v[130:133], v[210:213], v[78:81]
	v_lshlrev_b32_e32 v219, 7, v219
	v_mfma_f32_16x16x32_bf16 v[74:77], v[152:155], v[210:213], v[74:77]
	s_lshl_b32 s94, s4, 23
	v_mfma_f32_16x16x32_bf16 v[126:129], v[134:137], v[190:193], v[126:129]
	s_lshl_b32 s95, s46, 4
	v_mfma_f32_16x16x32_bf16 v[122:125], v[156:159], v[190:193], v[122:125]
	s_lshr_b32 s98, s33, 2
	v_mfma_f32_16x16x32_bf16 v[110:113], v[134:137], v[198:201], v[110:113]
	s_lshl_b32 s99, s98, 2
	v_mfma_f32_16x16x32_bf16 v[106:109], v[156:159], v[198:201], v[106:109]
	s_add_i32 s95, s95, s99
	v_mfma_f32_16x16x32_bf16 v[94:97], v[134:137], v[206:209], v[94:97]
	s_lshl_b32 s95, s95, 13
	v_mfma_f32_16x16x32_bf16 v[90:93], v[156:159], v[206:209], v[90:93]
	s_add_u32 s94, s94, s95
	v_mfma_f32_16x16x32_bf16 v[78:81], v[134:137], v[214:217], v[78:81]
	s_add_u32 s96, s36, s94
	v_mfma_f32_16x16x32_bf16 v[74:77], v[156:159], v[214:217], v[74:77]
	s_addc_u32 s97, s37, 0
	s_setprio 0
	s_setprio 1
	v_mfma_f32_16x16x32_bf16 v[118:121], v[166:169], v[186:189], v[118:121]
	s_lshl_b32 s94, s46, 8
	v_mfma_f32_16x16x32_bf16 v[114:117], v[174:177], v[186:189], v[114:117]
	s_lshr_b32 s95, s33, 2
	v_mfma_f32_16x16x32_bf16 v[102:105], v[166:169], v[194:197], v[102:105]
	s_lshl_b32 s95, s95, 6
	v_mfma_f32_16x16x32_bf16 v[98:101], v[174:177], v[194:197], v[98:101]
	s_add_i32 s94, s94, s95
	v_mfma_f32_16x16x32_bf16 v[86:89], v[166:169], v[202:205], v[86:89]
	s_lshl_b32 s94, s94, 7
	v_mfma_f32_16x16x32_bf16 v[82:85], v[174:177], v[202:205], v[82:85]
	s_sub_i32 s95, s4, 12
	v_mfma_f32_16x16x32_bf16 v[70:73], v[166:169], v[210:213], v[70:73]
	s_lshl_b32 s95, s95, 2
	v_mfma_f32_16x16x32_bf16 v[66:69], v[174:177], v[210:213], v[66:69]
	s_add_i32 s95, s95, s93
	v_mfma_f32_16x16x32_bf16 v[118:121], v[170:173], v[190:193], v[118:121]
	s_lshl_b32 s95, s95, 3
	v_mfma_f32_16x16x32_bf16 v[114:117], v[182:185], v[190:193], v[114:117]
	s_add_u32 s94, s94, s95
	v_mfma_f32_16x16x32_bf16 v[102:105], v[170:173], v[198:201], v[102:105]
	s_add_u32 s98, s54, s94
	v_mfma_f32_16x16x32_bf16 v[98:101], v[182:185], v[198:201], v[98:101]
	s_addc_u32 s99, s55, 0
	v_mfma_f32_16x16x32_bf16 v[86:89], v[170:173], v[206:209], v[86:89]
	v_mov_b32_e32 v220, 0xbfb8aa3b
	v_mfma_f32_16x16x32_bf16 v[82:85], v[182:185], v[206:209], v[82:85]
	v_mov_b32_e32 v221, 0xbfb8aa3b
	v_mfma_f32_16x16x32_bf16 v[70:73], v[170:173], v[214:217], v[70:73]
	v_mov_b32_e32 v222, 1.0
	v_mfma_f32_16x16x32_bf16 v[66:69], v[182:185], v[214:217], v[66:69]
	v_mov_b32_e32 v223, 1.0
	s_setprio 0
	s_barrier
	s_add_u32 s70, s60, 0x4000
	s_addc_u32 s71, s61, 0
	s_add_i32 s90, s90, s15
	v_lshl_add_u64 v[178:179], s[70:71], 0, v[138:139]
	s_mov_b32 m0, s90
	ds_read_b128 v[186:189], v163 offset:49152
	ds_read_b128 v[190:193], v163 offset:50176
	ds_read_b128 v[194:197], v163 offset:51200
	ds_read_b128 v[198:201], v163 offset:52224
	ds_read_b128 v[202:205], v163 offset:53248
	ds_read_b128 v[206:209], v163 offset:54272
	ds_read_b128 v[210:213], v163 offset:55296
	ds_read_b128 v[214:217], v163 offset:56320
	global_load_lds_dwordx4 v[178:179], off
	s_add_i32 m0, s90, 0x2000
	s_add_u32 s60, s60, 0x84000
	v_lshl_add_u64 v[178:179], s[70:71], 0, v[140:141]
	s_addc_u32 s61, s61, 0
	s_add_i32 s70, s91, s15
	global_load_lds_dwordx4 v[178:179], off
	v_lshl_add_u64 v[178:179], s[60:61], 0, v[138:139]
	s_mov_b32 m0, s70
	s_nop 0
	global_load_lds_dwordx4 v[178:179], off
	v_lshl_add_u64 v[178:179], s[60:61], 0, v[140:141]
	s_add_i32 m0, s70, 0x2000
	s_nop 0
	global_load_lds_dwordx4 v[178:179], off
	v_lshl_add_u64 v[178:179], s[58:59], 0, v[138:139]
	s_mov_b32 m0, s79
	s_nop 0
	global_load_lds_dwordx4 v[178:179], off
	v_lshl_add_u64 v[178:179], s[58:59], 0, v[140:141]
	s_mov_b32 m0, s80
	s_nop 0
	global_load_lds_dwordx4 v[178:179], off
	s_lshr_b32 s94, s4, 2
	s_cmp_eq_u32 s94, 1
	s_cbranch_scc1 .Lepi_silu
	s_cmp_eq_u32 s94, 4
	s_cbranch_scc1 .Lepi_silu
	s_cmp_eq_u32 s94, 6
	s_cbranch_scc1 .Lepi_silu
	s_cmp_eq_u32 s94, 5
	s_cbranch_scc1 .Lepi_scale
	s_cmp_eq_u32 s94, 3
	s_cbranch_scc1 .Lepi_stats
; #define PG8_WAIT_V(n) asm volatile("s_waitcnt vmcnt(" #n ")" ::: "memory")
; template <class Epi, class Sched, bool ALIGN_EPI = false, bool SP2 = false, bool RS = false, bool BPRE = false>
; __device__ __forceinline__ void gemm_phase(PG8_LAS unsigned char* lds, const Gemm g, const Sched& S, const Epi& E, const float* rs_ss = nullptr, PG8_LAS float* rs_tab = nullptr) {
;     ...
;             PG8_LDA(At, 1, 1); PG8_STAGE(PG8_SB(1, 0), b3, voffB); PG8_STAGE(PG8_SB(1, 1), b3 + hstep, voffB); PG8_STAGE(PG8_SA(1, 0), a3, voffA);
;             PG8_WAIT_V(8); PG8_WAIT_L(0); PG8_BAR; PG8_MMA(1, 0, At, B0); PG8_MMA(1, 1, At, B1); PG8_BAR; PG8_SCHED;
;     __device__ __forceinline__ void operator()(const f32x4 (&acc)[2][2][4][2], const pg8::Unit& u, int wr, int wc, int fr, int fq, const LAS float* tab) const {
;     ...
; #pragma unroll
;         for (int ai = 0; ai < 2; ++ai)
; #pragma unroll
;             for (int m = 0; m < 4; ++m) {
;                 const int row = row0 + ai * 128 + m * 16;
;                 bf16_t* rowp = (mode == 0) ? base + (size_t)(row >> 4) * 4096 + (size_t)(wc * 512 + (row & 15) * 32 + 8 * fq) : base + (size_t)row * ldc + col0;
;                 const int bjstep = (mode == 0) ? 4 * 512 : 128;
;                 float s1 = 0.f, s2 = 0.f;
;                 const float f2 = (kind == 4) ? tab[512 + ai * 128 + wr * 64 + m * 16 + fr] : 1.0f;
; #pragma unroll
;                 for (int bj = 0; bj < 2; ++bj) {
;                     f32x4 v0 = acc[ai][bj][m][0], v1 = acc[ai][bj][m][1];
;                     if (kind == 1) {
; #pragma unroll
;                         for (int e = 0; e < 4; ++e) { v0[e] = silu_f(v0[e]); v1[e] = silu_f(v1[e]); }
;                     } else if (kind == 2) { v0 = v0 * QSCALE; v1 = v1 * QSCALE; }
;                     else if (kind == 3) {
; #pragma unroll
;                         for (int e = 0; e < 4; ++e) { s1 += v0[e] + v1[e]; s2 += v0[e] * v0[e] + v1[e] * v1[e]; }
;                     } else if (kind == 4) {
;                         v0 = v0 * f2; v1 = v1 * f2;
; #pragma unroll
;                         for (int e = 0; e < 4; ++e) s2 += v0[e] * v0[e] + v1[e] * v1[e];
;                     }
;                     u32x4 w; w.x = cvt_pk_bf16(v0[0], v0[1]); w.y = cvt_pk_bf16(v0[2], v0[3]); w.z = cvt_pk_bf16(v1[0], v1[1]); w.w = cvt_pk_bf16(v1[2], v1[3]);
;                     *(u32x4*)(rowp + bj * bjstep) = w;
;                 }
.Lepi_plain:
	s_waitcnt vmcnt(8)
	s_waitcnt lgkmcnt(0)
	s_barrier
	s_setprio 1
	s_waitcnt lgkmcnt(0)
	v_mfma_f32_16x16x32_bf16 v[62:65], v[130:133], v[186:189], v[62:65]
	v_cvt_pk_bf16_f32 v232, v126, v127
	v_cvt_pk_bf16_f32 v233, v128, v129
	v_mfma_f32_16x16x32_bf16 v[58:61], v[152:155], v[186:189], v[58:61]
	v_cvt_pk_bf16_f32 v234, v122, v123
	v_cvt_pk_bf16_f32 v235, v124, v125
	v_mfma_f32_16x16x32_bf16 v[46:49], v[130:133], v[194:197], v[46:49]
	global_store_dwordx4 v218, v[232:235], s[96:97]
	s_add_u32 s96, s96, 0x1000
	s_addc_u32 s97, s97, 0
	v_cvt_pk_bf16_f32 v236, v118, v119
	v_mfma_f32_16x16x32_bf16 v[42:45], v[152:155], v[194:197], v[42:45]
	v_cvt_pk_bf16_f32 v237, v120, v121
	v_cvt_pk_bf16_f32 v238, v114, v115
	v_mfma_f32_16x16x32_bf16 v[30:33], v[130:133], v[202:205], v[30:33]
	v_cvt_pk_bf16_f32 v239, v116, v117
	global_store_dwordx4 v218, v[236:239], s[96:97]
	s_add_u32 s96, s96, 0x1000
	s_addc_u32 s97, s97, 0
	v_mfma_f32_16x16x32_bf16 v[26:29], v[152:155], v[202:205], v[26:29]
	v_cvt_pk_bf16_f32 v232, v110, v111
	v_cvt_pk_bf16_f32 v233, v112, v113
	v_mfma_f32_16x16x32_bf16 v[14:17], v[130:133], v[210:213], v[14:17]
	v_cvt_pk_bf16_f32 v234, v106, v107
	v_cvt_pk_bf16_f32 v235, v108, v109
	v_mfma_f32_16x16x32_bf16 v[10:13], v[152:155], v[210:213], v[10:13]
	global_store_dwordx4 v218, v[232:235], s[96:97]
	s_add_u32 s96, s96, 0x1000
	s_addc_u32 s97, s97, 0
	v_cvt_pk_bf16_f32 v236, v102, v103
	v_mfma_f32_16x16x32_bf16 v[62:65], v[134:137], v[190:193], v[62:65]
	v_cvt_pk_bf16_f32 v237, v104, v105
	v_mfma_f32_16x16x32_bf16 v[58:61], v[156:159], v[190:193], v[58:61]
	v_cvt_pk_bf16_f32 v238, v98, v99
	v_mfma_f32_16x16x32_bf16 v[46:49], v[134:137], v[198:201], v[46:49]
	v_cvt_pk_bf16_f32 v239, v100, v101
	v_mfma_f32_16x16x32_bf16 v[42:45], v[156:159], v[198:201], v[42:45]
	global_store_dwordx4 v218, v[236:239], s[96:97]
	s_add_u32 s96, s96, 0x1000
	s_addc_u32 s97, s97, 0
	v_mfma_f32_16x16x32_bf16 v[30:33], v[134:137], v[206:209], v[30:33]
	v_cvt_pk_bf16_f32 v232, v94, v95
	v_mfma_f32_16x16x32_bf16 v[26:29], v[156:159], v[206:209], v[26:29]
	v_cvt_pk_bf16_f32 v233, v96, v97
	v_mfma_f32_16x16x32_bf16 v[14:17], v[134:137], v[214:217], v[14:17]
	v_cvt_pk_bf16_f32 v234, v90, v91
	v_mfma_f32_16x16x32_bf16 v[10:13], v[156:159], v[214:217], v[10:13]
	v_cvt_pk_bf16_f32 v235, v92, v93
	s_setprio 0
	s_setprio 1
	v_mfma_f32_16x16x32_bf16 v[54:57], v[166:169], v[186:189], v[54:57]
	global_store_dwordx4 v218, v[232:235], s[96:97]
	s_add_u32 s96, s96, 0x1000
	s_addc_u32 s97, s97, 0
	v_mfma_f32_16x16x32_bf16 v[50:53], v[174:177], v[186:189], v[50:53]
	v_cvt_pk_bf16_f32 v236, v86, v87
	v_mfma_f32_16x16x32_bf16 v[38:41], v[166:169], v[194:197], v[38:41]
	v_cvt_pk_bf16_f32 v237, v88, v89
	v_mfma_f32_16x16x32_bf16 v[34:37], v[174:177], v[194:197], v[34:37]
	v_cvt_pk_bf16_f32 v238, v82, v83
	v_mfma_f32_16x16x32_bf16 v[22:25], v[166:169], v[202:205], v[22:25]
	v_cvt_pk_bf16_f32 v239, v84, v85
	v_mfma_f32_16x16x32_bf16 v[18:21], v[174:177], v[202:205], v[18:21]
	global_store_dwordx4 v218, v[236:239], s[96:97]
	s_add_u32 s96, s96, 0x1000
	s_addc_u32 s97, s97, 0
	v_mfma_f32_16x16x32_bf16 v[6:9], v[166:169], v[210:213], v[6:9]
	v_cvt_pk_bf16_f32 v232, v78, v79
	v_mfma_f32_16x16x32_bf16 v[2:5], v[174:177], v[210:213], v[2:5]
	v_cvt_pk_bf16_f32 v233, v80, v81
	v_mfma_f32_16x16x32_bf16 v[54:57], v[170:173], v[190:193], v[54:57]
	v_cvt_pk_bf16_f32 v234, v74, v75
	v_mfma_f32_16x16x32_bf16 v[50:53], v[182:185], v[190:193], v[50:53]
	v_cvt_pk_bf16_f32 v235, v76, v77
	v_mfma_f32_16x16x32_bf16 v[38:41], v[170:173], v[198:201], v[38:41]
	global_store_dwordx4 v218, v[232:235], s[96:97]
	s_add_u32 s96, s96, 0x1000
	s_addc_u32 s97, s97, 0
	v_mfma_f32_16x16x32_bf16 v[34:37], v[182:185], v[198:201], v[34:37]
	v_cvt_pk_bf16_f32 v236, v70, v71
	v_mfma_f32_16x16x32_bf16 v[22:25], v[170:173], v[206:209], v[22:25]
	v_cvt_pk_bf16_f32 v237, v72, v73
	v_mfma_f32_16x16x32_bf16 v[18:21], v[182:185], v[206:209], v[18:21]
	v_cvt_pk_bf16_f32 v238, v66, v67
	v_mfma_f32_16x16x32_bf16 v[6:9], v[170:173], v[214:217], v[6:9]
	v_cvt_pk_bf16_f32 v239, v68, v69
	v_mfma_f32_16x16x32_bf16 v[2:5], v[182:185], v[214:217], v[2:5]
	global_store_dwordx4 v218, v[236:239], s[96:97]
	s_add_u32 s96, s96, 0x1000
	s_addc_u32 s97, s97, 0
	s_add_u32 s96, s96, 0x8000
	s_addc_u32 s97, s97, 0
	s_setprio 0
	s_barrier
	s_add_i32 s89, s89, 2
	s_add_u32 s56, s56, 0x8000
	s_addc_u32 s57, s57, 0
	s_add_u32 s87, s87, 0x8000
	s_addc_u32 s88, s88, 0
	s_and_b64 vcc, exec, s[12:13]
	s_cbranch_vccz .Lepi_plain_al
	s_barrier
.Lepi_plain_al:
	v_cvt_pk_bf16_f32 v232, v62, v63
	v_cvt_pk_bf16_f32 v233, v64, v65
	v_cvt_pk_bf16_f32 v234, v58, v59
	v_cvt_pk_bf16_f32 v235, v60, v61
	global_store_dwordx4 v218, v[232:235], s[96:97]
	s_add_u32 s96, s96, 0x1000
	s_addc_u32 s97, s97, 0
	v_cvt_pk_bf16_f32 v236, v54, v55
	v_cvt_pk_bf16_f32 v237, v56, v57
	v_cvt_pk_bf16_f32 v238, v50, v51
	v_cvt_pk_bf16_f32 v239, v52, v53
	global_store_dwordx4 v218, v[236:239], s[96:97]
	s_add_u32 s96, s96, 0x1000
	s_addc_u32 s97, s97, 0
	v_cvt_pk_bf16_f32 v232, v46, v47
	v_cvt_pk_bf16_f32 v233, v48, v49
	v_cvt_pk_bf16_f32 v234, v42, v43
	v_cvt_pk_bf16_f32 v235, v44, v45
	global_store_dwordx4 v218, v[232:235], s[96:97]
	s_add_u32 s96, s96, 0x1000
	s_addc_u32 s97, s97, 0
	v_cvt_pk_bf16_f32 v236, v38, v39
	v_cvt_pk_bf16_f32 v237, v40, v41
	v_cvt_pk_bf16_f32 v238, v34, v35
	v_cvt_pk_bf16_f32 v239, v36, v37
	global_store_dwordx4 v218, v[236:239], s[96:97]
	s_add_u32 s96, s96, 0x1000
	s_addc_u32 s97, s97, 0
	v_cvt_pk_bf16_f32 v232, v30, v31
	v_cvt_pk_bf16_f32 v233, v32, v33
	v_cvt_pk_bf16_f32 v234, v26, v27
	v_cvt_pk_bf16_f32 v235, v28, v29
	global_store_dwordx4 v218, v[232:235], s[96:97]
	s_add_u32 s96, s96, 0x1000
	s_addc_u32 s97, s97, 0
	v_cvt_pk_bf16_f32 v236, v22, v23
	v_cvt_pk_bf16_f32 v237, v24, v25
	v_cvt_pk_bf16_f32 v238, v18, v19
	v_cvt_pk_bf16_f32 v239, v20, v21
	global_store_dwordx4 v218, v[236:239], s[96:97]
	s_add_u32 s96, s96, 0x1000
	s_addc_u32 s97, s97, 0
	v_cvt_pk_bf16_f32 v232, v14, v15
	v_cvt_pk_bf16_f32 v233, v16, v17
	v_cvt_pk_bf16_f32 v234, v10, v11
	v_cvt_pk_bf16_f32 v235, v12, v13
	global_store_dwordx4 v218, v[232:235], s[96:97]
	s_add_u32 s96, s96, 0x1000
	s_addc_u32 s97, s97, 0
	v_cvt_pk_bf16_f32 v236, v6, v7
	v_cvt_pk_bf16_f32 v237, v8, v9
	v_cvt_pk_bf16_f32 v238, v2, v3
	v_cvt_pk_bf16_f32 v239, v4, v5
	global_store_dwordx4 v218, v[236:239], s[96:97]
	s_add_u32 s96, s96, 0x1000
	s_addc_u32 s97, s97, 0
	s_branch .LBB0_391
; __device__ __forceinline__ unsigned cvt_pk_bf16(float lo, float hi) { unsigned r; asm volatile("v_cvt_pk_bf16_f32 %0, %1, %2" : "=v"(r) : "v"(lo), "v"(hi)); return r; }
; #define PG8_STAGE(bufoff, gbase, voff) do { _Pragma("unroll") for (int _i = 0; _i < 2; ++_i) \
;         __builtin_amdgcn_global_load_lds((const unsigned*)((const char*)(gbase) + (voff)[_i]), (PG8_LAS unsigned*)(lds + (bufoff) + ldsw + _i * 8192), 16, 0, 0); } while (0)
; #define PG8_LDA(dst, b, h) do { _Pragma("unroll") for (int m = 0; m < 4; ++m) _Pragma("unroll") for (int k = 0; k < 2; ++k) dst[m][k] = *(const PG8_LAS bf16x8*)(lds + PG8_SA(b, h) + aoff + m * 2048 + k * 1024); } while (0)
; template <class Epi, class Sched, bool ALIGN_EPI = false, bool SP2 = false, bool RS = false, bool BPRE = false>
; __device__ __forceinline__ void gemm_phase(PG8_LAS unsigned char* lds, const Gemm g, const Sched& S, const Epi& E, const float* rs_ss = nullptr, PG8_LAS float* rs_tab = nullptr) {
;     ...
;             PG8_LDA(At, 1, 1); PG8_STAGE(PG8_SB(1, 0), b3, voffB); PG8_STAGE(PG8_SB(1, 1), b3 + hstep, voffB); PG8_STAGE(PG8_SA(1, 0), a3, voffA);
;             PG8_WAIT_V(8); PG8_WAIT_L(0); PG8_BAR; PG8_MMA(1, 0, At, B0); PG8_MMA(1, 1, At, B1); PG8_BAR; PG8_SCHED;
;     __device__ __forceinline__ void operator()(const f32x4 (&acc)[2][2][4][2], const pg8::Unit& u, int wr, int wc, int fr, int fq, const LAS float* tab) const {
;     ...
;                 for (int bj = 0; bj < 2; ++bj) {
;                     f32x4 v0 = acc[ai][bj][m][0], v1 = acc[ai][bj][m][1];
;                     if (kind == 1) {
; #pragma unroll
;                         for (int e = 0; e < 4; ++e) { v0[e] = silu_f(v0[e]); v1[e] = silu_f(v1[e]); }
;                     } else if (kind == 2) { v0 = v0 * QSCALE; v1 = v1 * QSCALE; }
;                     else if (kind == 3) {
; #pragma unroll
;                         for (int e = 0; e < 4; ++e) { s1 += v0[e] + v1[e]; s2 += v0[e] * v0[e] + v1[e] * v1[e]; }
;                     } else if (kind == 4) {
;                         v0 = v0 * f2; v1 = v1 * f2;
; #pragma unroll
;                         for (int e = 0; e < 4; ++e) s2 += v0[e] * v0[e] + v1[e] * v1[e];
;                     }
;                     u32x4 w; w.x = cvt_pk_bf16(v0[0], v0[1]); w.y = cvt_pk_bf16(v0[2], v0[3]); w.z = cvt_pk_bf16(v1[0], v1[1]); w.w = cvt_pk_bf16(v1[2], v1[3]);
;                     *(u32x4*)(rowp + bj * bjstep) = w;
.Lepi_silu:
	s_waitcnt vmcnt(8)
	s_waitcnt lgkmcnt(0)
	s_barrier
	s_setprio 1
	s_waitcnt lgkmcnt(0)
	v_mfma_f32_16x16x32_bf16 v[62:65], v[130:133], v[186:189], v[62:65]
	v_pk_mul_f32 v[224:225], v[126:127], v[220:221]
	v_pk_mul_f32 v[226:227], v[128:129], v[220:221]
	v_pk_mul_f32 v[228:229], v[122:123], v[220:221]
	v_pk_mul_f32 v[230:231], v[124:125], v[220:221]
	v_exp_f32_e32 v224, v224
	v_exp_f32_e32 v225, v225
	v_exp_f32_e32 v226, v226
	v_exp_f32_e32 v227, v227
	v_exp_f32_e32 v228, v228
	v_mfma_f32_16x16x32_bf16 v[58:61], v[152:155], v[186:189], v[58:61]
	v_exp_f32_e32 v229, v229
	v_exp_f32_e32 v230, v230
	v_exp_f32_e32 v231, v231
	v_pk_add_f32 v[224:225], v[224:225], v[222:223]
	v_pk_add_f32 v[226:227], v[226:227], v[222:223]
	v_pk_add_f32 v[228:229], v[228:229], v[222:223]
	v_pk_add_f32 v[230:231], v[230:231], v[222:223]
	v_rcp_f32_e32 v224, v224
	v_rcp_f32_e32 v225, v225
	v_mfma_f32_16x16x32_bf16 v[46:49], v[130:133], v[194:197], v[46:49]
	v_rcp_f32_e32 v226, v226
	v_rcp_f32_e32 v227, v227
	v_rcp_f32_e32 v228, v228
	v_rcp_f32_e32 v229, v229
	v_rcp_f32_e32 v230, v230
	v_rcp_f32_e32 v231, v231
	v_pk_mul_f32 v[126:127], v[126:127], v[224:225]
	v_pk_mul_f32 v[128:129], v[128:129], v[226:227]
	v_pk_mul_f32 v[122:123], v[122:123], v[228:229]
	v_mfma_f32_16x16x32_bf16 v[42:45], v[152:155], v[194:197], v[42:45]
	v_pk_mul_f32 v[124:125], v[124:125], v[230:231]
	v_cvt_pk_bf16_f32 v232, v126, v127
	v_cvt_pk_bf16_f32 v233, v128, v129
	v_cvt_pk_bf16_f32 v234, v122, v123
	v_cvt_pk_bf16_f32 v235, v124, v125
	global_store_dwordx4 v218, v[232:235], s[96:97]
	s_add_u32 s96, s96, 0x1000
	s_addc_u32 s97, s97, 0
	v_pk_mul_f32 v[224:225], v[118:119], v[220:221]
	v_pk_mul_f32 v[226:227], v[120:121], v[220:221]
	v_pk_mul_f32 v[228:229], v[114:115], v[220:221]
	v_mfma_f32_16x16x32_bf16 v[30:33], v[130:133], v[202:205], v[30:33]
	v_pk_mul_f32 v[230:231], v[116:117], v[220:221]
	v_exp_f32_e32 v224, v224
	v_exp_f32_e32 v225, v225
	v_exp_f32_e32 v226, v226
	v_exp_f32_e32 v227, v227
	v_exp_f32_e32 v228, v228
	v_exp_f32_e32 v229, v229
	v_exp_f32_e32 v230, v230
	v_exp_f32_e32 v231, v231
	v_mfma_f32_16x16x32_bf16 v[26:29], v[152:155], v[202:205], v[26:29]
	v_pk_add_f32 v[224:225], v[224:225], v[222:223]
	v_pk_add_f32 v[226:227], v[226:227], v[222:223]
	v_pk_add_f32 v[228:229], v[228:229], v[222:223]
	v_pk_add_f32 v[230:231], v[230:231], v[222:223]
	v_rcp_f32_e32 v224, v224
	v_rcp_f32_e32 v225, v225
	v_rcp_f32_e32 v226, v226
	v_rcp_f32_e32 v227, v227
	v_rcp_f32_e32 v228, v228
	v_mfma_f32_16x16x32_bf16 v[14:17], v[130:133], v[210:213], v[14:17]
	v_rcp_f32_e32 v229, v229
	v_rcp_f32_e32 v230, v230
	v_rcp_f32_e32 v231, v231
	v_pk_mul_f32 v[118:119], v[118:119], v[224:225]
	v_pk_mul_f32 v[120:121], v[120:121], v[226:227]
	v_pk_mul_f32 v[114:115], v[114:115], v[228:229]
	v_pk_mul_f32 v[116:117], v[116:117], v[230:231]
	v_cvt_pk_bf16_f32 v236, v118, v119
	v_cvt_pk_bf16_f32 v237, v120, v121
	v_mfma_f32_16x16x32_bf16 v[10:13], v[152:155], v[210:213], v[10:13]
	v_cvt_pk_bf16_f32 v238, v114, v115
	v_cvt_pk_bf16_f32 v239, v116, v117
	global_store_dwordx4 v218, v[236:239], s[96:97]
	s_add_u32 s96, s96, 0x1000
	s_addc_u32 s97, s97, 0
	v_pk_mul_f32 v[224:225], v[110:111], v[220:221]
	v_pk_mul_f32 v[226:227], v[112:113], v[220:221]
	v_pk_mul_f32 v[228:229], v[106:107], v[220:221]
	v_pk_mul_f32 v[230:231], v[108:109], v[220:221]
	v_exp_f32_e32 v224, v224
	v_exp_f32_e32 v225, v225
	v_mfma_f32_16x16x32_bf16 v[62:65], v[134:137], v[190:193], v[62:65]
	v_exp_f32_e32 v226, v226
	v_exp_f32_e32 v227, v227
	v_exp_f32_e32 v228, v228
	v_exp_f32_e32 v229, v229
	v_exp_f32_e32 v230, v230
	v_exp_f32_e32 v231, v231
	v_pk_add_f32 v[224:225], v[224:225], v[222:223]
	v_pk_add_f32 v[226:227], v[226:227], v[222:223]
	v_mfma_f32_16x16x32_bf16 v[58:61], v[156:159], v[190:193], v[58:61]
	v_pk_add_f32 v[228:229], v[228:229], v[222:223]
	v_pk_add_f32 v[230:231], v[230:231], v[222:223]
	v_rcp_f32_e32 v224, v224
	v_rcp_f32_e32 v225, v225
	v_rcp_f32_e32 v226, v226
	v_rcp_f32_e32 v227, v227
	v_rcp_f32_e32 v228, v228
	v_rcp_f32_e32 v229, v229
	v_mfma_f32_16x16x32_bf16 v[46:49], v[134:137], v[198:201], v[46:49]
	v_rcp_f32_e32 v230, v230
	v_rcp_f32_e32 v231, v231
	v_pk_mul_f32 v[110:111], v[110:111], v[224:225]
	v_pk_mul_f32 v[112:113], v[112:113], v[226:227]
	v_pk_mul_f32 v[106:107], v[106:107], v[228:229]
	v_pk_mul_f32 v[108:109], v[108:109], v[230:231]
	v_cvt_pk_bf16_f32 v232, v110, v111
	v_cvt_pk_bf16_f32 v233, v112, v113
	v_mfma_f32_16x16x32_bf16 v[42:45], v[156:159], v[198:201], v[42:45]
	v_cvt_pk_bf16_f32 v234, v106, v107
	v_cvt_pk_bf16_f32 v235, v108, v109
	global_store_dwordx4 v218, v[232:235], s[96:97]
	s_add_u32 s96, s96, 0x1000
	s_addc_u32 s97, s97, 0
	v_pk_mul_f32 v[224:225], v[102:103], v[220:221]
	v_pk_mul_f32 v[226:227], v[104:105], v[220:221]
	v_pk_mul_f32 v[228:229], v[98:99], v[220:221]
	v_pk_mul_f32 v[230:231], v[100:101], v[220:221]
	v_exp_f32_e32 v224, v224
	v_mfma_f32_16x16x32_bf16 v[30:33], v[134:137], v[206:209], v[30:33]
	v_exp_f32_e32 v225, v225
	v_exp_f32_e32 v226, v226
	v_exp_f32_e32 v227, v227
	v_exp_f32_e32 v228, v228
	v_exp_f32_e32 v229, v229
	v_exp_f32_e32 v230, v230
	v_exp_f32_e32 v231, v231
	v_pk_add_f32 v[224:225], v[224:225], v[222:223]
	v_mfma_f32_16x16x32_bf16 v[26:29], v[156:159], v[206:209], v[26:29]
	v_pk_add_f32 v[226:227], v[226:227], v[222:223]
	v_pk_add_f32 v[228:229], v[228:229], v[222:223]
	v_pk_add_f32 v[230:231], v[230:231], v[222:223]
	v_rcp_f32_e32 v224, v224
	v_rcp_f32_e32 v225, v225
	v_rcp_f32_e32 v226, v226
	v_rcp_f32_e32 v227, v227
	v_rcp_f32_e32 v228, v228
	v_mfma_f32_16x16x32_bf16 v[14:17], v[134:137], v[214:217], v[14:17]
	v_rcp_f32_e32 v229, v229
; __device__ __forceinline__ unsigned cvt_pk_bf16(float lo, float hi) { unsigned r; asm volatile("v_cvt_pk_bf16_f32 %0, %1, %2" : "=v"(r) : "v"(lo), "v"(hi)); return r; }
; #define PG8_STAGE(bufoff, gbase, voff) do { _Pragma("unroll") for (int _i = 0; _i < 2; ++_i) \
;         __builtin_amdgcn_global_load_lds((const unsigned*)((const char*)(gbase) + (voff)[_i]), (PG8_LAS unsigned*)(lds + (bufoff) + ldsw + _i * 8192), 16, 0, 0); } while (0)
; #define PG8_LDA(dst, b, h) do { _Pragma("unroll") for (int m = 0; m < 4; ++m) _Pragma("unroll") for (int k = 0; k < 2; ++k) dst[m][k] = *(const PG8_LAS bf16x8*)(lds + PG8_SA(b, h) + aoff + m * 2048 + k * 1024); } while (0)
; template <class Epi, class Sched, bool ALIGN_EPI = false, bool SP2 = false, bool RS = false, bool BPRE = false>
; __device__ __forceinline__ void gemm_phase(PG8_LAS unsigned char* lds, const Gemm g, const Sched& S, const Epi& E, const float* rs_ss = nullptr, PG8_LAS float* rs_tab = nullptr) {
;     ...
;             PG8_LDA(At, 1, 1); PG8_STAGE(PG8_SB(1, 0), b3, voffB); PG8_STAGE(PG8_SB(1, 1), b3 + hstep, voffB); PG8_STAGE(PG8_SA(1, 0), a3, voffA);
;             PG8_WAIT_V(8); PG8_WAIT_L(0); PG8_BAR; PG8_MMA(1, 0, At, B0); PG8_MMA(1, 1, At, B1); PG8_BAR; PG8_SCHED;
;     __device__ __forceinline__ void operator()(const f32x4 (&acc)[2][2][4][2], const pg8::Unit& u, int wr, int wc, int fr, int fq, const LAS float* tab) const {
;     ...
;                 for (int bj = 0; bj < 2; ++bj) {
;                     f32x4 v0 = acc[ai][bj][m][0], v1 = acc[ai][bj][m][1];
;                     if (kind == 1) {
; #pragma unroll
;                         for (int e = 0; e < 4; ++e) { v0[e] = silu_f(v0[e]); v1[e] = silu_f(v1[e]); }
;                     } else if (kind == 2) { v0 = v0 * QSCALE; v1 = v1 * QSCALE; }
;                     else if (kind == 3) {
; #pragma unroll
;                         for (int e = 0; e < 4; ++e) { s1 += v0[e] + v1[e]; s2 += v0[e] * v0[e] + v1[e] * v1[e]; }
;                     } else if (kind == 4) {
;                         v0 = v0 * f2; v1 = v1 * f2;
; #pragma unroll
;                         for (int e = 0; e < 4; ++e) s2 += v0[e] * v0[e] + v1[e] * v1[e];
;                     }
;                     u32x4 w; w.x = cvt_pk_bf16(v0[0], v0[1]); w.y = cvt_pk_bf16(v0[2], v0[3]); w.z = cvt_pk_bf16(v1[0], v1[1]); w.w = cvt_pk_bf16(v1[2], v1[3]);
;                     *(u32x4*)(rowp + bj * bjstep) = w;
	v_rcp_f32_e32 v230, v230
	v_rcp_f32_e32 v231, v231
	v_pk_mul_f32 v[102:103], v[102:103], v[224:225]
	v_pk_mul_f32 v[104:105], v[104:105], v[226:227]
	v_pk_mul_f32 v[98:99], v[98:99], v[228:229]
	v_pk_mul_f32 v[100:101], v[100:101], v[230:231]
	v_cvt_pk_bf16_f32 v236, v102, v103
	v_mfma_f32_16x16x32_bf16 v[10:13], v[156:159], v[214:217], v[10:13]
	v_cvt_pk_bf16_f32 v237, v104, v105
	v_cvt_pk_bf16_f32 v238, v98, v99
	v_cvt_pk_bf16_f32 v239, v100, v101
	global_store_dwordx4 v218, v[236:239], s[96:97]
	s_add_u32 s96, s96, 0x1000
	s_addc_u32 s97, s97, 0
	v_pk_mul_f32 v[224:225], v[94:95], v[220:221]
	v_pk_mul_f32 v[226:227], v[96:97], v[220:221]
	v_pk_mul_f32 v[228:229], v[90:91], v[220:221]
	v_pk_mul_f32 v[230:231], v[92:93], v[220:221]
	s_setprio 0
	s_setprio 1
	v_mfma_f32_16x16x32_bf16 v[54:57], v[166:169], v[186:189], v[54:57]
	v_exp_f32_e32 v224, v224
	v_exp_f32_e32 v225, v225
	v_exp_f32_e32 v226, v226
	v_exp_f32_e32 v227, v227
	v_exp_f32_e32 v228, v228
	v_exp_f32_e32 v229, v229
	v_exp_f32_e32 v230, v230
	v_exp_f32_e32 v231, v231
	v_mfma_f32_16x16x32_bf16 v[50:53], v[174:177], v[186:189], v[50:53]
	v_pk_add_f32 v[224:225], v[224:225], v[222:223]
	v_pk_add_f32 v[226:227], v[226:227], v[222:223]
	v_pk_add_f32 v[228:229], v[228:229], v[222:223]
	v_pk_add_f32 v[230:231], v[230:231], v[222:223]
	v_rcp_f32_e32 v224, v224
	v_rcp_f32_e32 v225, v225
	v_rcp_f32_e32 v226, v226
	v_rcp_f32_e32 v227, v227
	v_mfma_f32_16x16x32_bf16 v[38:41], v[166:169], v[194:197], v[38:41]
	v_rcp_f32_e32 v228, v228
	v_rcp_f32_e32 v229, v229
	v_rcp_f32_e32 v230, v230
	v_rcp_f32_e32 v231, v231
	v_pk_mul_f32 v[94:95], v[94:95], v[224:225]
	v_pk_mul_f32 v[96:97], v[96:97], v[226:227]
	v_pk_mul_f32 v[90:91], v[90:91], v[228:229]
	v_pk_mul_f32 v[92:93], v[92:93], v[230:231]
	v_mfma_f32_16x16x32_bf16 v[34:37], v[174:177], v[194:197], v[34:37]
	v_cvt_pk_bf16_f32 v232, v94, v95
	v_cvt_pk_bf16_f32 v233, v96, v97
	v_cvt_pk_bf16_f32 v234, v90, v91
	v_cvt_pk_bf16_f32 v235, v92, v93
	global_store_dwordx4 v218, v[232:235], s[96:97]
	s_add_u32 s96, s96, 0x1000
	s_addc_u32 s97, s97, 0
	v_pk_mul_f32 v[224:225], v[86:87], v[220:221]
	v_pk_mul_f32 v[226:227], v[88:89], v[220:221]
	v_pk_mul_f32 v[228:229], v[82:83], v[220:221]
	v_mfma_f32_16x16x32_bf16 v[22:25], v[166:169], v[202:205], v[22:25]
	v_pk_mul_f32 v[230:231], v[84:85], v[220:221]
	v_exp_f32_e32 v224, v224
	v_exp_f32_e32 v225, v225
	v_exp_f32_e32 v226, v226
	v_exp_f32_e32 v227, v227
	v_exp_f32_e32 v228, v228
	v_exp_f32_e32 v229, v229
	v_exp_f32_e32 v230, v230
	v_mfma_f32_16x16x32_bf16 v[18:21], v[174:177], v[202:205], v[18:21]
	v_exp_f32_e32 v231, v231
	v_pk_add_f32 v[224:225], v[224:225], v[222:223]
	v_pk_add_f32 v[226:227], v[226:227], v[222:223]
	v_pk_add_f32 v[228:229], v[228:229], v[222:223]
	v_pk_add_f32 v[230:231], v[230:231], v[222:223]
	v_rcp_f32_e32 v224, v224
	v_rcp_f32_e32 v225, v225
	v_rcp_f32_e32 v226, v226
	v_mfma_f32_16x16x32_bf16 v[6:9], v[166:169], v[210:213], v[6:9]
	v_rcp_f32_e32 v227, v227
	v_rcp_f32_e32 v228, v228
	v_rcp_f32_e32 v229, v229
	v_rcp_f32_e32 v230, v230
	v_rcp_f32_e32 v231, v231
	v_pk_mul_f32 v[86:87], v[86:87], v[224:225]
	v_pk_mul_f32 v[88:89], v[88:89], v[226:227]
	v_pk_mul_f32 v[82:83], v[82:83], v[228:229]
	v_mfma_f32_16x16x32_bf16 v[2:5], v[174:177], v[210:213], v[2:5]
	v_pk_mul_f32 v[84:85], v[84:85], v[230:231]
	v_cvt_pk_bf16_f32 v236, v86, v87
	v_cvt_pk_bf16_f32 v237, v88, v89
	v_cvt_pk_bf16_f32 v238, v82, v83
	v_cvt_pk_bf16_f32 v239, v84, v85
	global_store_dwordx4 v218, v[236:239], s[96:97]
	s_add_u32 s96, s96, 0x1000
	s_addc_u32 s97, s97, 0
	v_pk_mul_f32 v[224:225], v[78:79], v[220:221]
	v_pk_mul_f32 v[226:227], v[80:81], v[220:221]
	v_mfma_f32_16x16x32_bf16 v[54:57], v[170:173], v[190:193], v[54:57]
	v_pk_mul_f32 v[228:229], v[74:75], v[220:221]
	v_pk_mul_f32 v[230:231], v[76:77], v[220:221]
	v_exp_f32_e32 v224, v224
	v_exp_f32_e32 v225, v225
	v_exp_f32_e32 v226, v226
	v_exp_f32_e32 v227, v227
	v_exp_f32_e32 v228, v228
	v_exp_f32_e32 v229, v229
	v_mfma_f32_16x16x32_bf16 v[50:53], v[182:185], v[190:193], v[50:53]
	v_exp_f32_e32 v230, v230
	v_exp_f32_e32 v231, v231
	v_pk_add_f32 v[224:225], v[224:225], v[222:223]
	v_pk_add_f32 v[226:227], v[226:227], v[222:223]
	v_pk_add_f32 v[228:229], v[228:229], v[222:223]
	v_pk_add_f32 v[230:231], v[230:231], v[222:223]
	v_rcp_f32_e32 v224, v224
	v_rcp_f32_e32 v225, v225
	v_mfma_f32_16x16x32_bf16 v[38:41], v[170:173], v[198:201], v[38:41]
	v_rcp_f32_e32 v226, v226
	v_rcp_f32_e32 v227, v227
	v_rcp_f32_e32 v228, v228
	v_rcp_f32_e32 v229, v229
	v_rcp_f32_e32 v230, v230
	v_rcp_f32_e32 v231, v231
	v_pk_mul_f32 v[78:79], v[78:79], v[224:225]
	v_pk_mul_f32 v[80:81], v[80:81], v[226:227]
	v_mfma_f32_16x16x32_bf16 v[34:37], v[182:185], v[198:201], v[34:37]
	v_pk_mul_f32 v[74:75], v[74:75], v[228:229]
	v_pk_mul_f32 v[76:77], v[76:77], v[230:231]
	v_cvt_pk_bf16_f32 v232, v78, v79
	v_cvt_pk_bf16_f32 v233, v80, v81
	v_cvt_pk_bf16_f32 v234, v74, v75
	v_cvt_pk_bf16_f32 v235, v76, v77
	global_store_dwordx4 v218, v[232:235], s[96:97]
	s_add_u32 s96, s96, 0x1000
	s_addc_u32 s97, s97, 0
	v_pk_mul_f32 v[224:225], v[70:71], v[220:221]
	v_mfma_f32_16x16x32_bf16 v[22:25], v[170:173], v[206:209], v[22:25]
	v_pk_mul_f32 v[226:227], v[72:73], v[220:221]
	v_pk_mul_f32 v[228:229], v[66:67], v[220:221]
	v_pk_mul_f32 v[230:231], v[68:69], v[220:221]
	v_exp_f32_e32 v224, v224
	v_exp_f32_e32 v225, v225
	v_exp_f32_e32 v226, v226
	v_exp_f32_e32 v227, v227
	v_exp_f32_e32 v228, v228
	v_mfma_f32_16x16x32_bf16 v[18:21], v[182:185], v[206:209], v[18:21]
	v_exp_f32_e32 v229, v229
	v_exp_f32_e32 v230, v230
	v_exp_f32_e32 v231, v231
	v_pk_add_f32 v[224:225], v[224:225], v[222:223]
	v_pk_add_f32 v[226:227], v[226:227], v[222:223]
	v_pk_add_f32 v[228:229], v[228:229], v[222:223]
	v_pk_add_f32 v[230:231], v[230:231], v[222:223]
	v_rcp_f32_e32 v224, v224
	v_mfma_f32_16x16x32_bf16 v[6:9], v[170:173], v[214:217], v[6:9]
	v_rcp_f32_e32 v225, v225
	v_rcp_f32_e32 v226, v226
	v_rcp_f32_e32 v227, v227
	v_rcp_f32_e32 v228, v228
	v_rcp_f32_e32 v229, v229
	v_rcp_f32_e32 v230, v230
	v_rcp_f32_e32 v231, v231
	v_pk_mul_f32 v[70:71], v[70:71], v[224:225]
	v_mfma_f32_16x16x32_bf16 v[2:5], v[182:185], v[214:217], v[2:5]
	v_pk_mul_f32 v[72:73], v[72:73], v[226:227]
	v_pk_mul_f32 v[66:67], v[66:67], v[228:229]
	v_pk_mul_f32 v[68:69], v[68:69], v[230:231]
	v_cvt_pk_bf16_f32 v236, v70, v71
	v_cvt_pk_bf16_f32 v237, v72, v73
	v_cvt_pk_bf16_f32 v238, v66, v67
	v_cvt_pk_bf16_f32 v239, v68, v69
	global_store_dwordx4 v218, v[236:239], s[96:97]
	s_add_u32 s96, s96, 0x1000
	s_addc_u32 s97, s97, 0
	s_add_u32 s96, s96, 0x8000
	s_addc_u32 s97, s97, 0
	s_setprio 0
	s_barrier
	s_add_i32 s89, s89, 2
	s_add_u32 s56, s56, 0x8000
	s_addc_u32 s57, s57, 0
	s_add_u32 s87, s87, 0x8000
	s_addc_u32 s88, s88, 0
	s_and_b64 vcc, exec, s[12:13]
	s_cbranch_vccz .Lepi_silu_al
	s_barrier
; __device__ __forceinline__ unsigned cvt_pk_bf16(float lo, float hi) { unsigned r; asm volatile("v_cvt_pk_bf16_f32 %0, %1, %2" : "=v"(r) : "v"(lo), "v"(hi)); return r; }
; __device__ __forceinline__ float silu_f(float x) { return x * __builtin_amdgcn_rcpf(1.0f + __builtin_amdgcn_exp2f(-x * LOG2E)); }
;     __device__ __forceinline__ void operator()(const f32x4 (&acc)[2][2][4][2], const pg8::Unit& u, int wr, int wc, int fr, int fq, const LAS float* tab) const {
;     ...
;                 for (int bj = 0; bj < 2; ++bj) {
;                     f32x4 v0 = acc[ai][bj][m][0], v1 = acc[ai][bj][m][1];
;                     if (kind == 1) {
; #pragma unroll
;                         for (int e = 0; e < 4; ++e) { v0[e] = silu_f(v0[e]); v1[e] = silu_f(v1[e]); }
;                     } else if (kind == 2) { v0 = v0 * QSCALE; v1 = v1 * QSCALE; }
;                     else if (kind == 3) {
; #pragma unroll
;                         for (int e = 0; e < 4; ++e) { s1 += v0[e] + v1[e]; s2 += v0[e] * v0[e] + v1[e] * v1[e]; }
;                     } else if (kind == 4) {
;                         v0 = v0 * f2; v1 = v1 * f2;
; #pragma unroll
;                         for (int e = 0; e < 4; ++e) s2 += v0[e] * v0[e] + v1[e] * v1[e];
;                     }
;                     u32x4 w; w.x = cvt_pk_bf16(v0[0], v0[1]); w.y = cvt_pk_bf16(v0[2], v0[3]); w.z = cvt_pk_bf16(v1[0], v1[1]); w.w = cvt_pk_bf16(v1[2], v1[3]);
;                     *(u32x4*)(rowp + bj * bjstep) = w;
.Lepi_silu_al:
	v_pk_mul_f32 v[224:225], v[62:63], v[220:221]
	v_pk_mul_f32 v[226:227], v[64:65], v[220:221]
	v_pk_mul_f32 v[228:229], v[58:59], v[220:221]
	v_pk_mul_f32 v[230:231], v[60:61], v[220:221]
	v_exp_f32_e32 v224, v224
	v_exp_f32_e32 v225, v225
	v_exp_f32_e32 v226, v226
	v_exp_f32_e32 v227, v227
	v_exp_f32_e32 v228, v228
	v_exp_f32_e32 v229, v229
	v_exp_f32_e32 v230, v230
	v_exp_f32_e32 v231, v231
	v_pk_add_f32 v[224:225], v[224:225], v[222:223]
	v_pk_add_f32 v[226:227], v[226:227], v[222:223]
	v_pk_add_f32 v[228:229], v[228:229], v[222:223]
	v_pk_add_f32 v[230:231], v[230:231], v[222:223]
	v_rcp_f32_e32 v224, v224
	v_rcp_f32_e32 v225, v225
	v_rcp_f32_e32 v226, v226
	v_rcp_f32_e32 v227, v227
	v_rcp_f32_e32 v228, v228
	v_rcp_f32_e32 v229, v229
	v_rcp_f32_e32 v230, v230
	v_rcp_f32_e32 v231, v231
	v_pk_mul_f32 v[62:63], v[62:63], v[224:225]
	v_pk_mul_f32 v[64:65], v[64:65], v[226:227]
	v_pk_mul_f32 v[58:59], v[58:59], v[228:229]
	v_pk_mul_f32 v[60:61], v[60:61], v[230:231]
	v_cvt_pk_bf16_f32 v232, v62, v63
	v_cvt_pk_bf16_f32 v233, v64, v65
	v_cvt_pk_bf16_f32 v234, v58, v59
	v_cvt_pk_bf16_f32 v235, v60, v61
	global_store_dwordx4 v218, v[232:235], s[96:97]
	s_add_u32 s96, s96, 0x1000
	s_addc_u32 s97, s97, 0
	v_pk_mul_f32 v[224:225], v[54:55], v[220:221]
	v_pk_mul_f32 v[226:227], v[56:57], v[220:221]
	v_pk_mul_f32 v[228:229], v[50:51], v[220:221]
	v_pk_mul_f32 v[230:231], v[52:53], v[220:221]
	v_exp_f32_e32 v224, v224
	v_exp_f32_e32 v225, v225
	v_exp_f32_e32 v226, v226
	v_exp_f32_e32 v227, v227
	v_exp_f32_e32 v228, v228
	v_exp_f32_e32 v229, v229
	v_exp_f32_e32 v230, v230
	v_exp_f32_e32 v231, v231
	v_pk_add_f32 v[224:225], v[224:225], v[222:223]
	v_pk_add_f32 v[226:227], v[226:227], v[222:223]
	v_pk_add_f32 v[228:229], v[228:229], v[222:223]
	v_pk_add_f32 v[230:231], v[230:231], v[222:223]
	v_rcp_f32_e32 v224, v224
	v_rcp_f32_e32 v225, v225
	v_rcp_f32_e32 v226, v226
	v_rcp_f32_e32 v227, v227
	v_rcp_f32_e32 v228, v228
	v_rcp_f32_e32 v229, v229
	v_rcp_f32_e32 v230, v230
	v_rcp_f32_e32 v231, v231
	v_pk_mul_f32 v[54:55], v[54:55], v[224:225]
	v_pk_mul_f32 v[56:57], v[56:57], v[226:227]
	v_pk_mul_f32 v[50:51], v[50:51], v[228:229]
	v_pk_mul_f32 v[52:53], v[52:53], v[230:231]
	v_cvt_pk_bf16_f32 v236, v54, v55
	v_cvt_pk_bf16_f32 v237, v56, v57
	v_cvt_pk_bf16_f32 v238, v50, v51
	v_cvt_pk_bf16_f32 v239, v52, v53
	global_store_dwordx4 v218, v[236:239], s[96:97]
	s_add_u32 s96, s96, 0x1000
	s_addc_u32 s97, s97, 0
	v_pk_mul_f32 v[224:225], v[46:47], v[220:221]
	v_pk_mul_f32 v[226:227], v[48:49], v[220:221]
	v_pk_mul_f32 v[228:229], v[42:43], v[220:221]
	v_pk_mul_f32 v[230:231], v[44:45], v[220:221]
	v_exp_f32_e32 v224, v224
	v_exp_f32_e32 v225, v225
	v_exp_f32_e32 v226, v226
	v_exp_f32_e32 v227, v227
	v_exp_f32_e32 v228, v228
	v_exp_f32_e32 v229, v229
	v_exp_f32_e32 v230, v230
	v_exp_f32_e32 v231, v231
	v_pk_add_f32 v[224:225], v[224:225], v[222:223]
	v_pk_add_f32 v[226:227], v[226:227], v[222:223]
	v_pk_add_f32 v[228:229], v[228:229], v[222:223]
	v_pk_add_f32 v[230:231], v[230:231], v[222:223]
	v_rcp_f32_e32 v224, v224
	v_rcp_f32_e32 v225, v225
	v_rcp_f32_e32 v226, v226
	v_rcp_f32_e32 v227, v227
	v_rcp_f32_e32 v228, v228
	v_rcp_f32_e32 v229, v229
	v_rcp_f32_e32 v230, v230
	v_rcp_f32_e32 v231, v231
	v_pk_mul_f32 v[46:47], v[46:47], v[224:225]
	v_pk_mul_f32 v[48:49], v[48:49], v[226:227]
	v_pk_mul_f32 v[42:43], v[42:43], v[228:229]
	v_pk_mul_f32 v[44:45], v[44:45], v[230:231]
	v_cvt_pk_bf16_f32 v232, v46, v47
	v_cvt_pk_bf16_f32 v233, v48, v49
	v_cvt_pk_bf16_f32 v234, v42, v43
	v_cvt_pk_bf16_f32 v235, v44, v45
	global_store_dwordx4 v218, v[232:235], s[96:97]
	s_add_u32 s96, s96, 0x1000
	s_addc_u32 s97, s97, 0
	v_pk_mul_f32 v[224:225], v[38:39], v[220:221]
	v_pk_mul_f32 v[226:227], v[40:41], v[220:221]
	v_pk_mul_f32 v[228:229], v[34:35], v[220:221]
	v_pk_mul_f32 v[230:231], v[36:37], v[220:221]
	v_exp_f32_e32 v224, v224
	v_exp_f32_e32 v225, v225
	v_exp_f32_e32 v226, v226
	v_exp_f32_e32 v227, v227
	v_exp_f32_e32 v228, v228
	v_exp_f32_e32 v229, v229
	v_exp_f32_e32 v230, v230
	v_exp_f32_e32 v231, v231
	v_pk_add_f32 v[224:225], v[224:225], v[222:223]
	v_pk_add_f32 v[226:227], v[226:227], v[222:223]
	v_pk_add_f32 v[228:229], v[228:229], v[222:223]
	v_pk_add_f32 v[230:231], v[230:231], v[222:223]
	v_rcp_f32_e32 v224, v224
	v_rcp_f32_e32 v225, v225
	v_rcp_f32_e32 v226, v226
	v_rcp_f32_e32 v227, v227
	v_rcp_f32_e32 v228, v228
	v_rcp_f32_e32 v229, v229
	v_rcp_f32_e32 v230, v230
	v_rcp_f32_e32 v231, v231
	v_pk_mul_f32 v[38:39], v[38:39], v[224:225]
	v_pk_mul_f32 v[40:41], v[40:41], v[226:227]
	v_pk_mul_f32 v[34:35], v[34:35], v[228:229]
	v_pk_mul_f32 v[36:37], v[36:37], v[230:231]
	v_cvt_pk_bf16_f32 v236, v38, v39
	v_cvt_pk_bf16_f32 v237, v40, v41
	v_cvt_pk_bf16_f32 v238, v34, v35
	v_cvt_pk_bf16_f32 v239, v36, v37
	global_store_dwordx4 v218, v[236:239], s[96:97]
	s_add_u32 s96, s96, 0x1000
	s_addc_u32 s97, s97, 0
	v_pk_mul_f32 v[224:225], v[30:31], v[220:221]
	v_pk_mul_f32 v[226:227], v[32:33], v[220:221]
	v_pk_mul_f32 v[228:229], v[26:27], v[220:221]
	v_pk_mul_f32 v[230:231], v[28:29], v[220:221]
	v_exp_f32_e32 v224, v224
	v_exp_f32_e32 v225, v225
	v_exp_f32_e32 v226, v226
	v_exp_f32_e32 v227, v227
	v_exp_f32_e32 v228, v228
	v_exp_f32_e32 v229, v229
	v_exp_f32_e32 v230, v230
	v_exp_f32_e32 v231, v231
	v_pk_add_f32 v[224:225], v[224:225], v[222:223]
	v_pk_add_f32 v[226:227], v[226:227], v[222:223]
	v_pk_add_f32 v[228:229], v[228:229], v[222:223]
	v_pk_add_f32 v[230:231], v[230:231], v[222:223]
	v_rcp_f32_e32 v224, v224
	v_rcp_f32_e32 v225, v225
	v_rcp_f32_e32 v226, v226
	v_rcp_f32_e32 v227, v227
	v_rcp_f32_e32 v228, v228
	v_rcp_f32_e32 v229, v229
; __device__ __forceinline__ unsigned cvt_pk_bf16(float lo, float hi) { unsigned r; asm volatile("v_cvt_pk_bf16_f32 %0, %1, %2" : "=v"(r) : "v"(lo), "v"(hi)); return r; }
; __device__ __forceinline__ float silu_f(float x) { return x * __builtin_amdgcn_rcpf(1.0f + __builtin_amdgcn_exp2f(-x * LOG2E)); }
;     __device__ __forceinline__ void operator()(const f32x4 (&acc)[2][2][4][2], const pg8::Unit& u, int wr, int wc, int fr, int fq, const LAS float* tab) const {
;     ...
;         for (int ai = 0; ai < 2; ++ai)
; #pragma unroll
;             for (int m = 0; m < 4; ++m) {
;                 const int row = row0 + ai * 128 + m * 16;
;                 bf16_t* rowp = (mode == 0) ? base + (size_t)(row >> 4) * 4096 + (size_t)(wc * 512 + (row & 15) * 32 + 8 * fq) : base + (size_t)row * ldc + col0;
;                 const int bjstep = (mode == 0) ? 4 * 512 : 128;
;                 float s1 = 0.f, s2 = 0.f;
;                 const float f2 = (kind == 4) ? tab[512 + ai * 128 + wr * 64 + m * 16 + fr] : 1.0f;
; #pragma unroll
;                 for (int bj = 0; bj < 2; ++bj) {
;                     f32x4 v0 = acc[ai][bj][m][0], v1 = acc[ai][bj][m][1];
;                     if (kind == 1) {
; #pragma unroll
;                         for (int e = 0; e < 4; ++e) { v0[e] = silu_f(v0[e]); v1[e] = silu_f(v1[e]); }
;                     } else if (kind == 2) { v0 = v0 * QSCALE; v1 = v1 * QSCALE; }
;                     else if (kind == 3) {
; #pragma unroll
;                         for (int e = 0; e < 4; ++e) { s1 += v0[e] + v1[e]; s2 += v0[e] * v0[e] + v1[e] * v1[e]; }
;                     } else if (kind == 4) {
;                         v0 = v0 * f2; v1 = v1 * f2;
; #pragma unroll
;                         for (int e = 0; e < 4; ++e) s2 += v0[e] * v0[e] + v1[e] * v1[e];
;                     }
;                     u32x4 w; w.x = cvt_pk_bf16(v0[0], v0[1]); w.y = cvt_pk_bf16(v0[2], v0[3]); w.z = cvt_pk_bf16(v1[0], v1[1]); w.w = cvt_pk_bf16(v1[2], v1[3]);
;                     *(u32x4*)(rowp + bj * bjstep) = w;
;                 }
	v_rcp_f32_e32 v230, v230
	v_rcp_f32_e32 v231, v231
	v_pk_mul_f32 v[30:31], v[30:31], v[224:225]
	v_pk_mul_f32 v[32:33], v[32:33], v[226:227]
	v_pk_mul_f32 v[26:27], v[26:27], v[228:229]
	v_pk_mul_f32 v[28:29], v[28:29], v[230:231]
	v_cvt_pk_bf16_f32 v232, v30, v31
	v_cvt_pk_bf16_f32 v233, v32, v33
	v_cvt_pk_bf16_f32 v234, v26, v27
	v_cvt_pk_bf16_f32 v235, v28, v29
	global_store_dwordx4 v218, v[232:235], s[96:97]
	s_add_u32 s96, s96, 0x1000
	s_addc_u32 s97, s97, 0
	v_pk_mul_f32 v[224:225], v[22:23], v[220:221]
	v_pk_mul_f32 v[226:227], v[24:25], v[220:221]
	v_pk_mul_f32 v[228:229], v[18:19], v[220:221]
	v_pk_mul_f32 v[230:231], v[20:21], v[220:221]
	v_exp_f32_e32 v224, v224
	v_exp_f32_e32 v225, v225
	v_exp_f32_e32 v226, v226
	v_exp_f32_e32 v227, v227
	v_exp_f32_e32 v228, v228
	v_exp_f32_e32 v229, v229
	v_exp_f32_e32 v230, v230
	v_exp_f32_e32 v231, v231
	v_pk_add_f32 v[224:225], v[224:225], v[222:223]
	v_pk_add_f32 v[226:227], v[226:227], v[222:223]
	v_pk_add_f32 v[228:229], v[228:229], v[222:223]
	v_pk_add_f32 v[230:231], v[230:231], v[222:223]
	v_rcp_f32_e32 v224, v224
	v_rcp_f32_e32 v225, v225
	v_rcp_f32_e32 v226, v226
	v_rcp_f32_e32 v227, v227
	v_rcp_f32_e32 v228, v228
	v_rcp_f32_e32 v229, v229
	v_rcp_f32_e32 v230, v230
	v_rcp_f32_e32 v231, v231
	v_pk_mul_f32 v[22:23], v[22:23], v[224:225]
	v_pk_mul_f32 v[24:25], v[24:25], v[226:227]
	v_pk_mul_f32 v[18:19], v[18:19], v[228:229]
	v_pk_mul_f32 v[20:21], v[20:21], v[230:231]
	v_cvt_pk_bf16_f32 v236, v22, v23
	v_cvt_pk_bf16_f32 v237, v24, v25
	v_cvt_pk_bf16_f32 v238, v18, v19
	v_cvt_pk_bf16_f32 v239, v20, v21
	global_store_dwordx4 v218, v[236:239], s[96:97]
	s_add_u32 s96, s96, 0x1000
	s_addc_u32 s97, s97, 0
	v_pk_mul_f32 v[224:225], v[14:15], v[220:221]
	v_pk_mul_f32 v[226:227], v[16:17], v[220:221]
	v_pk_mul_f32 v[228:229], v[10:11], v[220:221]
	v_pk_mul_f32 v[230:231], v[12:13], v[220:221]
	v_exp_f32_e32 v224, v224
	v_exp_f32_e32 v225, v225
	v_exp_f32_e32 v226, v226
	v_exp_f32_e32 v227, v227
	v_exp_f32_e32 v228, v228
	v_exp_f32_e32 v229, v229
	v_exp_f32_e32 v230, v230
	v_exp_f32_e32 v231, v231
	v_pk_add_f32 v[224:225], v[224:225], v[222:223]
	v_pk_add_f32 v[226:227], v[226:227], v[222:223]
	v_pk_add_f32 v[228:229], v[228:229], v[222:223]
	v_pk_add_f32 v[230:231], v[230:231], v[222:223]
	v_rcp_f32_e32 v224, v224
	v_rcp_f32_e32 v225, v225
	v_rcp_f32_e32 v226, v226
	v_rcp_f32_e32 v227, v227
	v_rcp_f32_e32 v228, v228
	v_rcp_f32_e32 v229, v229
	v_rcp_f32_e32 v230, v230
	v_rcp_f32_e32 v231, v231
	v_pk_mul_f32 v[14:15], v[14:15], v[224:225]
	v_pk_mul_f32 v[16:17], v[16:17], v[226:227]
	v_pk_mul_f32 v[10:11], v[10:11], v[228:229]
	v_pk_mul_f32 v[12:13], v[12:13], v[230:231]
	v_cvt_pk_bf16_f32 v232, v14, v15
	v_cvt_pk_bf16_f32 v233, v16, v17
	v_cvt_pk_bf16_f32 v234, v10, v11
	v_cvt_pk_bf16_f32 v235, v12, v13
	global_store_dwordx4 v218, v[232:235], s[96:97]
	s_add_u32 s96, s96, 0x1000
	s_addc_u32 s97, s97, 0
	v_pk_mul_f32 v[224:225], v[6:7], v[220:221]
	v_pk_mul_f32 v[226:227], v[8:9], v[220:221]
	v_pk_mul_f32 v[228:229], v[2:3], v[220:221]
	v_pk_mul_f32 v[230:231], v[4:5], v[220:221]
	v_exp_f32_e32 v224, v224
	v_exp_f32_e32 v225, v225
	v_exp_f32_e32 v226, v226
	v_exp_f32_e32 v227, v227
	v_exp_f32_e32 v228, v228
	v_exp_f32_e32 v229, v229
	v_exp_f32_e32 v230, v230
	v_exp_f32_e32 v231, v231
	v_pk_add_f32 v[224:225], v[224:225], v[222:223]
	v_pk_add_f32 v[226:227], v[226:227], v[222:223]
	v_pk_add_f32 v[228:229], v[228:229], v[222:223]
	v_pk_add_f32 v[230:231], v[230:231], v[222:223]
	v_rcp_f32_e32 v224, v224
	v_rcp_f32_e32 v225, v225
	v_rcp_f32_e32 v226, v226
	v_rcp_f32_e32 v227, v227
	v_rcp_f32_e32 v228, v228
	v_rcp_f32_e32 v229, v229
	v_rcp_f32_e32 v230, v230
	v_rcp_f32_e32 v231, v231
	v_pk_mul_f32 v[6:7], v[6:7], v[224:225]
	v_pk_mul_f32 v[8:9], v[8:9], v[226:227]
	v_pk_mul_f32 v[2:3], v[2:3], v[228:229]
	v_pk_mul_f32 v[4:5], v[4:5], v[230:231]
	v_cvt_pk_bf16_f32 v236, v6, v7
	v_cvt_pk_bf16_f32 v237, v8, v9
	v_cvt_pk_bf16_f32 v238, v2, v3
	v_cvt_pk_bf16_f32 v239, v4, v5
	global_store_dwordx4 v218, v[236:239], s[96:97]
	s_add_u32 s96, s96, 0x1000
	s_addc_u32 s97, s97, 0
	s_branch .LBB0_391
.Lepi_scale:
	s_waitcnt vmcnt(8)
	s_waitcnt lgkmcnt(0)
	s_barrier
	s_setprio 1
	s_waitcnt lgkmcnt(0)
	v_mfma_f32_16x16x32_bf16 v[62:65], v[130:133], v[186:189], v[62:65]
	v_pk_mul_f32 v[126:127], v[126:127], s[14:15] op_sel_hi:[1,0]
	v_pk_mul_f32 v[128:129], v[128:129], s[14:15] op_sel_hi:[1,0]
	v_pk_mul_f32 v[122:123], v[122:123], s[14:15] op_sel_hi:[1,0]
	v_mfma_f32_16x16x32_bf16 v[58:61], v[152:155], v[186:189], v[58:61]
	v_pk_mul_f32 v[124:125], v[124:125], s[14:15] op_sel_hi:[1,0]
	v_cvt_pk_bf16_f32 v232, v126, v127
	v_cvt_pk_bf16_f32 v233, v128, v129
	v_mfma_f32_16x16x32_bf16 v[46:49], v[130:133], v[194:197], v[46:49]
	v_cvt_pk_bf16_f32 v234, v122, v123
	v_cvt_pk_bf16_f32 v235, v124, v125
	global_store_dwordx4 v218, v[232:235], s[96:97]
	s_add_u32 s96, s96, 0x1000
	s_addc_u32 s97, s97, 0
	v_mfma_f32_16x16x32_bf16 v[42:45], v[152:155], v[194:197], v[42:45]
	v_pk_mul_f32 v[118:119], v[118:119], s[14:15] op_sel_hi:[1,0]
	v_pk_mul_f32 v[120:121], v[120:121], s[14:15] op_sel_hi:[1,0]
	v_pk_mul_f32 v[114:115], v[114:115], s[14:15] op_sel_hi:[1,0]
	v_mfma_f32_16x16x32_bf16 v[30:33], v[130:133], v[202:205], v[30:33]
	v_pk_mul_f32 v[116:117], v[116:117], s[14:15] op_sel_hi:[1,0]
	v_cvt_pk_bf16_f32 v236, v118, v119
	v_cvt_pk_bf16_f32 v237, v120, v121
	v_mfma_f32_16x16x32_bf16 v[26:29], v[152:155], v[202:205], v[26:29]
	v_cvt_pk_bf16_f32 v238, v114, v115
	v_cvt_pk_bf16_f32 v239, v116, v117
	global_store_dwordx4 v218, v[236:239], s[96:97]
	s_add_u32 s96, s96, 0x1000
	s_addc_u32 s97, s97, 0
; #define PG8_WAIT_V(n) asm volatile("s_waitcnt vmcnt(" #n ")" ::: "memory")
; template <class Epi, class Sched, bool ALIGN_EPI = false, bool SP2 = false, bool RS = false, bool BPRE = false>
; __device__ __forceinline__ void gemm_phase(PG8_LAS unsigned char* lds, const Gemm g, const Sched& S, const Epi& E, const float* rs_ss = nullptr, PG8_LAS float* rs_tab = nullptr) {
;     ...
;             PG8_LDA(At, 1, 1); PG8_STAGE(PG8_SB(1, 0), b3, voffB); PG8_STAGE(PG8_SB(1, 1), b3 + hstep, voffB); PG8_STAGE(PG8_SA(1, 0), a3, voffA);
;             PG8_WAIT_V(8); PG8_WAIT_L(0); PG8_BAR; PG8_MMA(1, 0, At, B0); PG8_MMA(1, 1, At, B1); PG8_BAR; PG8_SCHED;
;     __device__ __forceinline__ void operator()(const f32x4 (&acc)[2][2][4][2], const pg8::Unit& u, int wr, int wc, int fr, int fq, const LAS float* tab) const {
;     ...
;         for (int ai = 0; ai < 2; ++ai)
; #pragma unroll
;             for (int m = 0; m < 4; ++m) {
;                 const int row = row0 + ai * 128 + m * 16;
;                 bf16_t* rowp = (mode == 0) ? base + (size_t)(row >> 4) * 4096 + (size_t)(wc * 512 + (row & 15) * 32 + 8 * fq) : base + (size_t)row * ldc + col0;
;                 const int bjstep = (mode == 0) ? 4 * 512 : 128;
;                 float s1 = 0.f, s2 = 0.f;
;                 const float f2 = (kind == 4) ? tab[512 + ai * 128 + wr * 64 + m * 16 + fr] : 1.0f;
; #pragma unroll
;                 for (int bj = 0; bj < 2; ++bj) {
;                     f32x4 v0 = acc[ai][bj][m][0], v1 = acc[ai][bj][m][1];
;                     if (kind == 1) {
; #pragma unroll
;                         for (int e = 0; e < 4; ++e) { v0[e] = silu_f(v0[e]); v1[e] = silu_f(v1[e]); }
;                     } else if (kind == 2) { v0 = v0 * QSCALE; v1 = v1 * QSCALE; }
;                     else if (kind == 3) {
; #pragma unroll
;                         for (int e = 0; e < 4; ++e) { s1 += v0[e] + v1[e]; s2 += v0[e] * v0[e] + v1[e] * v1[e]; }
;                     } else if (kind == 4) {
;                         v0 = v0 * f2; v1 = v1 * f2;
; #pragma unroll
;                         for (int e = 0; e < 4; ++e) s2 += v0[e] * v0[e] + v1[e] * v1[e];
;                     }
;                     u32x4 w; w.x = cvt_pk_bf16(v0[0], v0[1]); w.y = cvt_pk_bf16(v0[2], v0[3]); w.z = cvt_pk_bf16(v1[0], v1[1]); w.w = cvt_pk_bf16(v1[2], v1[3]);
;                     *(u32x4*)(rowp + bj * bjstep) = w;
;                 }
	v_mfma_f32_16x16x32_bf16 v[14:17], v[130:133], v[210:213], v[14:17]
	v_pk_mul_f32 v[110:111], v[110:111], s[14:15] op_sel_hi:[1,0]
	v_pk_mul_f32 v[112:113], v[112:113], s[14:15] op_sel_hi:[1,0]
	v_pk_mul_f32 v[106:107], v[106:107], s[14:15] op_sel_hi:[1,0]
	v_mfma_f32_16x16x32_bf16 v[10:13], v[152:155], v[210:213], v[10:13]
	v_pk_mul_f32 v[108:109], v[108:109], s[14:15] op_sel_hi:[1,0]
	v_cvt_pk_bf16_f32 v232, v110, v111
	v_cvt_pk_bf16_f32 v233, v112, v113
	v_mfma_f32_16x16x32_bf16 v[62:65], v[134:137], v[190:193], v[62:65]
	v_cvt_pk_bf16_f32 v234, v106, v107
	v_cvt_pk_bf16_f32 v235, v108, v109
	v_mfma_f32_16x16x32_bf16 v[58:61], v[156:159], v[190:193], v[58:61]
	global_store_dwordx4 v218, v[232:235], s[96:97]
	s_add_u32 s96, s96, 0x1000
	s_addc_u32 s97, s97, 0
	v_pk_mul_f32 v[102:103], v[102:103], s[14:15] op_sel_hi:[1,0]
	v_mfma_f32_16x16x32_bf16 v[46:49], v[134:137], v[198:201], v[46:49]
	v_pk_mul_f32 v[104:105], v[104:105], s[14:15] op_sel_hi:[1,0]
	v_pk_mul_f32 v[98:99], v[98:99], s[14:15] op_sel_hi:[1,0]
	v_mfma_f32_16x16x32_bf16 v[42:45], v[156:159], v[198:201], v[42:45]
	v_pk_mul_f32 v[100:101], v[100:101], s[14:15] op_sel_hi:[1,0]
	v_cvt_pk_bf16_f32 v236, v102, v103
	v_mfma_f32_16x16x32_bf16 v[30:33], v[134:137], v[206:209], v[30:33]
	v_cvt_pk_bf16_f32 v237, v104, v105
	v_cvt_pk_bf16_f32 v238, v98, v99
	v_mfma_f32_16x16x32_bf16 v[26:29], v[156:159], v[206:209], v[26:29]
	v_cvt_pk_bf16_f32 v239, v100, v101
	global_store_dwordx4 v218, v[236:239], s[96:97]
	s_add_u32 s96, s96, 0x1000
	s_addc_u32 s97, s97, 0
	v_mfma_f32_16x16x32_bf16 v[14:17], v[134:137], v[214:217], v[14:17]
	v_pk_mul_f32 v[94:95], v[94:95], s[14:15] op_sel_hi:[1,0]
	v_pk_mul_f32 v[96:97], v[96:97], s[14:15] op_sel_hi:[1,0]
	v_mfma_f32_16x16x32_bf16 v[10:13], v[156:159], v[214:217], v[10:13]
	v_pk_mul_f32 v[90:91], v[90:91], s[14:15] op_sel_hi:[1,0]
	v_pk_mul_f32 v[92:93], v[92:93], s[14:15] op_sel_hi:[1,0]
	s_setprio 0
	s_setprio 1
	v_mfma_f32_16x16x32_bf16 v[54:57], v[166:169], v[186:189], v[54:57]
	v_cvt_pk_bf16_f32 v232, v94, v95
	v_cvt_pk_bf16_f32 v233, v96, v97
	v_mfma_f32_16x16x32_bf16 v[50:53], v[174:177], v[186:189], v[50:53]
	v_cvt_pk_bf16_f32 v234, v90, v91
	v_cvt_pk_bf16_f32 v235, v92, v93
	v_mfma_f32_16x16x32_bf16 v[38:41], v[166:169], v[194:197], v[38:41]
	global_store_dwordx4 v218, v[232:235], s[96:97]
	s_add_u32 s96, s96, 0x1000
	s_addc_u32 s97, s97, 0
	v_pk_mul_f32 v[86:87], v[86:87], s[14:15] op_sel_hi:[1,0]
	v_mfma_f32_16x16x32_bf16 v[34:37], v[174:177], v[194:197], v[34:37]
	v_pk_mul_f32 v[88:89], v[88:89], s[14:15] op_sel_hi:[1,0]
	v_pk_mul_f32 v[82:83], v[82:83], s[14:15] op_sel_hi:[1,0]
	v_mfma_f32_16x16x32_bf16 v[22:25], v[166:169], v[202:205], v[22:25]
	v_pk_mul_f32 v[84:85], v[84:85], s[14:15] op_sel_hi:[1,0]
	v_cvt_pk_bf16_f32 v236, v86, v87
	v_mfma_f32_16x16x32_bf16 v[18:21], v[174:177], v[202:205], v[18:21]
	v_cvt_pk_bf16_f32 v237, v88, v89
	v_cvt_pk_bf16_f32 v238, v82, v83
	v_mfma_f32_16x16x32_bf16 v[6:9], v[166:169], v[210:213], v[6:9]
	v_cvt_pk_bf16_f32 v239, v84, v85
	global_store_dwordx4 v218, v[236:239], s[96:97]
	s_add_u32 s96, s96, 0x1000
	s_addc_u32 s97, s97, 0
	v_mfma_f32_16x16x32_bf16 v[2:5], v[174:177], v[210:213], v[2:5]
	v_pk_mul_f32 v[78:79], v[78:79], s[14:15] op_sel_hi:[1,0]
	v_pk_mul_f32 v[80:81], v[80:81], s[14:15] op_sel_hi:[1,0]
	v_mfma_f32_16x16x32_bf16 v[54:57], v[170:173], v[190:193], v[54:57]
	v_pk_mul_f32 v[74:75], v[74:75], s[14:15] op_sel_hi:[1,0]
	v_pk_mul_f32 v[76:77], v[76:77], s[14:15] op_sel_hi:[1,0]
	v_mfma_f32_16x16x32_bf16 v[50:53], v[182:185], v[190:193], v[50:53]
	v_cvt_pk_bf16_f32 v232, v78, v79
	v_cvt_pk_bf16_f32 v233, v80, v81
	v_mfma_f32_16x16x32_bf16 v[38:41], v[170:173], v[198:201], v[38:41]
	v_cvt_pk_bf16_f32 v234, v74, v75
	v_cvt_pk_bf16_f32 v235, v76, v77
	v_mfma_f32_16x16x32_bf16 v[34:37], v[182:185], v[198:201], v[34:37]
	global_store_dwordx4 v218, v[232:235], s[96:97]
	s_add_u32 s96, s96, 0x1000
	s_addc_u32 s97, s97, 0
	v_pk_mul_f32 v[70:71], v[70:71], s[14:15] op_sel_hi:[1,0]
	v_mfma_f32_16x16x32_bf16 v[22:25], v[170:173], v[206:209], v[22:25]
	v_pk_mul_f32 v[72:73], v[72:73], s[14:15] op_sel_hi:[1,0]
	v_pk_mul_f32 v[66:67], v[66:67], s[14:15] op_sel_hi:[1,0]
	v_mfma_f32_16x16x32_bf16 v[18:21], v[182:185], v[206:209], v[18:21]
	v_pk_mul_f32 v[68:69], v[68:69], s[14:15] op_sel_hi:[1,0]
	v_cvt_pk_bf16_f32 v236, v70, v71
	v_mfma_f32_16x16x32_bf16 v[6:9], v[170:173], v[214:217], v[6:9]
	v_cvt_pk_bf16_f32 v237, v72, v73
	v_cvt_pk_bf16_f32 v238, v66, v67
	v_mfma_f32_16x16x32_bf16 v[2:5], v[182:185], v[214:217], v[2:5]
	v_cvt_pk_bf16_f32 v239, v68, v69
	global_store_dwordx4 v218, v[236:239], s[96:97]
	s_add_u32 s96, s96, 0x1000
	s_addc_u32 s97, s97, 0
	s_add_u32 s96, s96, 0x8000
	s_addc_u32 s97, s97, 0
	s_setprio 0
	s_barrier
	s_add_i32 s89, s89, 2
	s_add_u32 s56, s56, 0x8000
	s_addc_u32 s57, s57, 0
	s_add_u32 s87, s87, 0x8000
	s_addc_u32 s88, s88, 0
	s_and_b64 vcc, exec, s[12:13]
	s_cbranch_vccz .Lepi_scale_al
	s_barrier
; __device__ __forceinline__ unsigned cvt_pk_bf16(float lo, float hi) { unsigned r; asm volatile("v_cvt_pk_bf16_f32 %0, %1, %2" : "=v"(r) : "v"(lo), "v"(hi)); return r; }
; __device__ __forceinline__ float silu_f(float x) { return x * __builtin_amdgcn_rcpf(1.0f + __builtin_amdgcn_exp2f(-x * LOG2E)); }
;     __device__ __forceinline__ void operator()(const f32x4 (&acc)[2][2][4][2], const pg8::Unit& u, int wr, int wc, int fr, int fq, const LAS float* tab) const {
;     ...
;         for (int ai = 0; ai < 2; ++ai)
; #pragma unroll
;             for (int m = 0; m < 4; ++m) {
;                 const int row = row0 + ai * 128 + m * 16;
;                 bf16_t* rowp = (mode == 0) ? base + (size_t)(row >> 4) * 4096 + (size_t)(wc * 512 + (row & 15) * 32 + 8 * fq) : base + (size_t)row * ldc + col0;
;                 const int bjstep = (mode == 0) ? 4 * 512 : 128;
;                 float s1 = 0.f, s2 = 0.f;
;                 const float f2 = (kind == 4) ? tab[512 + ai * 128 + wr * 64 + m * 16 + fr] : 1.0f;
; #pragma unroll
;                 for (int bj = 0; bj < 2; ++bj) {
;                     f32x4 v0 = acc[ai][bj][m][0], v1 = acc[ai][bj][m][1];
;                     if (kind == 1) {
; #pragma unroll
;                         for (int e = 0; e < 4; ++e) { v0[e] = silu_f(v0[e]); v1[e] = silu_f(v1[e]); }
;                     } else if (kind == 2) { v0 = v0 * QSCALE; v1 = v1 * QSCALE; }
;                     else if (kind == 3) {
; #pragma unroll
;                         for (int e = 0; e < 4; ++e) { s1 += v0[e] + v1[e]; s2 += v0[e] * v0[e] + v1[e] * v1[e]; }
;                     } else if (kind == 4) {
;                         v0 = v0 * f2; v1 = v1 * f2;
; #pragma unroll
;                         for (int e = 0; e < 4; ++e) s2 += v0[e] * v0[e] + v1[e] * v1[e];
;                     }
;                     u32x4 w; w.x = cvt_pk_bf16(v0[0], v0[1]); w.y = cvt_pk_bf16(v0[2], v0[3]); w.z = cvt_pk_bf16(v1[0], v1[1]); w.w = cvt_pk_bf16(v1[2], v1[3]);
;                     *(u32x4*)(rowp + bj * bjstep) = w;
;                 }
;                 if (kind == 3) {
;                     s1 += __shfl_xor(s1, 16); s1 += __shfl_xor(s1, 32); s2 += __shfl_xor(s2, 16); s2 += __shfl_xor(s2, 32);
;                     if (fq == 0) { float* p = aux + (size_t)row * 32 + ((pn - 12) * 4 + wc) * 2; p[0] = s1; p[1] = s2; }
.Lepi_scale_al:
	v_pk_mul_f32 v[62:63], v[62:63], s[14:15] op_sel_hi:[1,0]
	v_pk_mul_f32 v[64:65], v[64:65], s[14:15] op_sel_hi:[1,0]
	v_pk_mul_f32 v[58:59], v[58:59], s[14:15] op_sel_hi:[1,0]
	v_pk_mul_f32 v[60:61], v[60:61], s[14:15] op_sel_hi:[1,0]
	v_cvt_pk_bf16_f32 v232, v62, v63
	v_cvt_pk_bf16_f32 v233, v64, v65
	v_cvt_pk_bf16_f32 v234, v58, v59
	v_cvt_pk_bf16_f32 v235, v60, v61
	global_store_dwordx4 v218, v[232:235], s[96:97]
	s_add_u32 s96, s96, 0x1000
	s_addc_u32 s97, s97, 0
	v_pk_mul_f32 v[54:55], v[54:55], s[14:15] op_sel_hi:[1,0]
	v_pk_mul_f32 v[56:57], v[56:57], s[14:15] op_sel_hi:[1,0]
	v_pk_mul_f32 v[50:51], v[50:51], s[14:15] op_sel_hi:[1,0]
	v_pk_mul_f32 v[52:53], v[52:53], s[14:15] op_sel_hi:[1,0]
	v_cvt_pk_bf16_f32 v236, v54, v55
	v_cvt_pk_bf16_f32 v237, v56, v57
	v_cvt_pk_bf16_f32 v238, v50, v51
	v_cvt_pk_bf16_f32 v239, v52, v53
	global_store_dwordx4 v218, v[236:239], s[96:97]
	s_add_u32 s96, s96, 0x1000
	s_addc_u32 s97, s97, 0
	v_pk_mul_f32 v[46:47], v[46:47], s[14:15] op_sel_hi:[1,0]
	v_pk_mul_f32 v[48:49], v[48:49], s[14:15] op_sel_hi:[1,0]
	v_pk_mul_f32 v[42:43], v[42:43], s[14:15] op_sel_hi:[1,0]
	v_pk_mul_f32 v[44:45], v[44:45], s[14:15] op_sel_hi:[1,0]
	v_cvt_pk_bf16_f32 v232, v46, v47
	v_cvt_pk_bf16_f32 v233, v48, v49
	v_cvt_pk_bf16_f32 v234, v42, v43
	v_cvt_pk_bf16_f32 v235, v44, v45
	global_store_dwordx4 v218, v[232:235], s[96:97]
	s_add_u32 s96, s96, 0x1000
	s_addc_u32 s97, s97, 0
	v_pk_mul_f32 v[38:39], v[38:39], s[14:15] op_sel_hi:[1,0]
	v_pk_mul_f32 v[40:41], v[40:41], s[14:15] op_sel_hi:[1,0]
	v_pk_mul_f32 v[34:35], v[34:35], s[14:15] op_sel_hi:[1,0]
	v_pk_mul_f32 v[36:37], v[36:37], s[14:15] op_sel_hi:[1,0]
	v_cvt_pk_bf16_f32 v236, v38, v39
	v_cvt_pk_bf16_f32 v237, v40, v41
	v_cvt_pk_bf16_f32 v238, v34, v35
	v_cvt_pk_bf16_f32 v239, v36, v37
	global_store_dwordx4 v218, v[236:239], s[96:97]
	s_add_u32 s96, s96, 0x1000
	s_addc_u32 s97, s97, 0
	v_pk_mul_f32 v[30:31], v[30:31], s[14:15] op_sel_hi:[1,0]
	v_pk_mul_f32 v[32:33], v[32:33], s[14:15] op_sel_hi:[1,0]
	v_pk_mul_f32 v[26:27], v[26:27], s[14:15] op_sel_hi:[1,0]
	v_pk_mul_f32 v[28:29], v[28:29], s[14:15] op_sel_hi:[1,0]
	v_cvt_pk_bf16_f32 v232, v30, v31
	v_cvt_pk_bf16_f32 v233, v32, v33
	v_cvt_pk_bf16_f32 v234, v26, v27
	v_cvt_pk_bf16_f32 v235, v28, v29
	global_store_dwordx4 v218, v[232:235], s[96:97]
	s_add_u32 s96, s96, 0x1000
	s_addc_u32 s97, s97, 0
	v_pk_mul_f32 v[22:23], v[22:23], s[14:15] op_sel_hi:[1,0]
	v_pk_mul_f32 v[24:25], v[24:25], s[14:15] op_sel_hi:[1,0]
	v_pk_mul_f32 v[18:19], v[18:19], s[14:15] op_sel_hi:[1,0]
	v_pk_mul_f32 v[20:21], v[20:21], s[14:15] op_sel_hi:[1,0]
	v_cvt_pk_bf16_f32 v236, v22, v23
	v_cvt_pk_bf16_f32 v237, v24, v25
	v_cvt_pk_bf16_f32 v238, v18, v19
	v_cvt_pk_bf16_f32 v239, v20, v21
	global_store_dwordx4 v218, v[236:239], s[96:97]
	s_add_u32 s96, s96, 0x1000
	s_addc_u32 s97, s97, 0
	v_pk_mul_f32 v[14:15], v[14:15], s[14:15] op_sel_hi:[1,0]
	v_pk_mul_f32 v[16:17], v[16:17], s[14:15] op_sel_hi:[1,0]
	v_pk_mul_f32 v[10:11], v[10:11], s[14:15] op_sel_hi:[1,0]
	v_pk_mul_f32 v[12:13], v[12:13], s[14:15] op_sel_hi:[1,0]
	v_cvt_pk_bf16_f32 v232, v14, v15
	v_cvt_pk_bf16_f32 v233, v16, v17
	v_cvt_pk_bf16_f32 v234, v10, v11
	v_cvt_pk_bf16_f32 v235, v12, v13
	global_store_dwordx4 v218, v[232:235], s[96:97]
	s_add_u32 s96, s96, 0x1000
	s_addc_u32 s97, s97, 0
	v_pk_mul_f32 v[6:7], v[6:7], s[14:15] op_sel_hi:[1,0]
	v_pk_mul_f32 v[8:9], v[8:9], s[14:15] op_sel_hi:[1,0]
	v_pk_mul_f32 v[2:3], v[2:3], s[14:15] op_sel_hi:[1,0]
	v_pk_mul_f32 v[4:5], v[4:5], s[14:15] op_sel_hi:[1,0]
	v_cvt_pk_bf16_f32 v236, v6, v7
	v_cvt_pk_bf16_f32 v237, v8, v9
	v_cvt_pk_bf16_f32 v238, v2, v3
	v_cvt_pk_bf16_f32 v239, v4, v5
	global_store_dwordx4 v218, v[236:239], s[96:97]
	s_add_u32 s96, s96, 0x1000
	s_addc_u32 s97, s97, 0
	s_branch .LBB0_391
.Lepi_stats:
	s_waitcnt vmcnt(8)
	s_waitcnt lgkmcnt(0)
	s_barrier
	s_setprio 1
	s_waitcnt lgkmcnt(0)
	v_mfma_f32_16x16x32_bf16 v[62:65], v[130:133], v[186:189], v[62:65]
	v_mov_b32_e32 v240, v126
	v_mov_b32_e32 v241, v127
	v_pk_mul_f32 v[242:243], v[126:127], v[126:127]
	v_pk_add_f32 v[240:241], v[240:241], v[128:129]
	v_pk_fma_f32 v[242:243], v[128:129], v[128:129], v[242:243]
	v_mfma_f32_16x16x32_bf16 v[58:61], v[152:155], v[186:189], v[58:61]
	v_pk_add_f32 v[240:241], v[240:241], v[122:123]
	v_pk_fma_f32 v[242:243], v[122:123], v[122:123], v[242:243]
	v_pk_add_f32 v[240:241], v[240:241], v[124:125]
	v_pk_fma_f32 v[242:243], v[124:125], v[124:125], v[242:243]
	v_pk_add_f32 v[240:241], v[240:241], v[118:119]
	v_mfma_f32_16x16x32_bf16 v[46:49], v[130:133], v[194:197], v[46:49]
	v_pk_fma_f32 v[242:243], v[118:119], v[118:119], v[242:243]
	v_pk_add_f32 v[240:241], v[240:241], v[120:121]
	v_pk_fma_f32 v[242:243], v[120:121], v[120:121], v[242:243]
	v_pk_add_f32 v[240:241], v[240:241], v[114:115]
	v_pk_fma_f32 v[242:243], v[114:115], v[114:115], v[242:243]
	v_mfma_f32_16x16x32_bf16 v[42:45], v[152:155], v[194:197], v[42:45]
	v_pk_add_f32 v[240:241], v[240:241], v[116:117]
	v_pk_fma_f32 v[242:243], v[116:117], v[116:117], v[242:243]
	v_add_f32_e32 v240, v240, v241
	v_add_f32_e32 v241, v242, v243
	v_mov_b32_e32 v242, v240
	v_mfma_f32_16x16x32_bf16 v[30:33], v[130:133], v[202:205], v[30:33]
	v_mov_b32_e32 v243, v241
	s_nop 1
	v_permlane16_swap_b32_e32 v242, v240
	v_permlane16_swap_b32_e32 v243, v241
	v_pk_add_f32 v[240:241], v[240:241], v[242:243]
	v_mov_b32_e32 v242, v240
	v_mov_b32_e32 v243, v241
	v_mfma_f32_16x16x32_bf16 v[26:29], v[152:155], v[202:205], v[26:29]
	s_nop 1
	v_permlane32_swap_b32_e32 v242, v240
	v_permlane32_swap_b32_e32 v243, v241
	v_pk_add_f32 v[244:245], v[240:241], v[242:243]
	v_cvt_pk_bf16_f32 v232, v126, v127
; __device__ __forceinline__ unsigned cvt_pk_bf16(float lo, float hi) { unsigned r; asm volatile("v_cvt_pk_bf16_f32 %0, %1, %2" : "=v"(r) : "v"(lo), "v"(hi)); return r; }
; #define PG8_STAGE(bufoff, gbase, voff) do { _Pragma("unroll") for (int _i = 0; _i < 2; ++_i) \
;         __builtin_amdgcn_global_load_lds((const unsigned*)((const char*)(gbase) + (voff)[_i]), (PG8_LAS unsigned*)(lds + (bufoff) + ldsw + _i * 8192), 16, 0, 0); } while (0)
; #define PG8_LDA(dst, b, h) do { _Pragma("unroll") for (int m = 0; m < 4; ++m) _Pragma("unroll") for (int k = 0; k < 2; ++k) dst[m][k] = *(const PG8_LAS bf16x8*)(lds + PG8_SA(b, h) + aoff + m * 2048 + k * 1024); } while (0)
; #define PG8_BAR __builtin_amdgcn_s_barrier()
; template <class Epi, class Sched, bool ALIGN_EPI = false, bool SP2 = false, bool RS = false, bool BPRE = false>
; __device__ __forceinline__ void gemm_phase(PG8_LAS unsigned char* lds, const Gemm g, const Sched& S, const Epi& E, const float* rs_ss = nullptr, PG8_LAS float* rs_tab = nullptr) {
;     ...
;             PG8_LDA(At, 1, 1); PG8_STAGE(PG8_SB(1, 0), b3, voffB); PG8_STAGE(PG8_SB(1, 1), b3 + hstep, voffB); PG8_STAGE(PG8_SA(1, 0), a3, voffA);
;             PG8_WAIT_V(8); PG8_WAIT_L(0); PG8_BAR; PG8_MMA(1, 0, At, B0); PG8_MMA(1, 1, At, B1); PG8_BAR; PG8_SCHED;
;     __device__ __forceinline__ void operator()(const f32x4 (&acc)[2][2][4][2], const pg8::Unit& u, int wr, int wc, int fr, int fq, const LAS float* tab) const {
;     ...
;                     else if (kind == 3) {
; #pragma unroll
;                         for (int e = 0; e < 4; ++e) { s1 += v0[e] + v1[e]; s2 += v0[e] * v0[e] + v1[e] * v1[e]; }
;                     } else if (kind == 4) {
;                         v0 = v0 * f2; v1 = v1 * f2;
; #pragma unroll
;                         for (int e = 0; e < 4; ++e) s2 += v0[e] * v0[e] + v1[e] * v1[e];
;                     }
;                     u32x4 w; w.x = cvt_pk_bf16(v0[0], v0[1]); w.y = cvt_pk_bf16(v0[2], v0[3]); w.z = cvt_pk_bf16(v1[0], v1[1]); w.w = cvt_pk_bf16(v1[2], v1[3]);
;                     *(u32x4*)(rowp + bj * bjstep) = w;
;                 }
;                 if (kind == 3) {
;                     s1 += __shfl_xor(s1, 16); s1 += __shfl_xor(s1, 32); s2 += __shfl_xor(s2, 16); s2 += __shfl_xor(s2, 32);
;                     if (fq == 0) { float* p = aux + (size_t)row * 32 + ((pn - 12) * 4 + wc) * 2; p[0] = s1; p[1] = s2; }
	v_cvt_pk_bf16_f32 v233, v128, v129
	v_cvt_pk_bf16_f32 v234, v122, v123
	v_mfma_f32_16x16x32_bf16 v[14:17], v[130:133], v[210:213], v[14:17]
	v_cvt_pk_bf16_f32 v235, v124, v125
	global_store_dwordx4 v218, v[232:235], s[96:97]
	s_add_u32 s96, s96, 0x1000
	s_addc_u32 s97, s97, 0
	v_cvt_pk_bf16_f32 v236, v118, v119
	v_cvt_pk_bf16_f32 v237, v120, v121
	v_cvt_pk_bf16_f32 v238, v114, v115
	v_mfma_f32_16x16x32_bf16 v[10:13], v[152:155], v[210:213], v[10:13]
	v_cvt_pk_bf16_f32 v239, v116, v117
	global_store_dwordx4 v218, v[236:239], s[96:97]
	s_add_u32 s96, s96, 0x1000
	s_addc_u32 s97, s97, 0
	s_and_saveexec_b64 vcc, s[0:1]
	global_store_dwordx2 v219, v[244:245], s[98:99]
	s_or_b64 exec, exec, vcc
	s_add_u32 s98, s98, 0x800
	s_addc_u32 s99, s99, 0
	v_mov_b32_e32 v240, v110
	v_mov_b32_e32 v241, v111
	v_mfma_f32_16x16x32_bf16 v[62:65], v[134:137], v[190:193], v[62:65]
	v_pk_mul_f32 v[242:243], v[110:111], v[110:111]
	v_pk_add_f32 v[240:241], v[240:241], v[112:113]
	v_pk_fma_f32 v[242:243], v[112:113], v[112:113], v[242:243]
	v_pk_add_f32 v[240:241], v[240:241], v[106:107]
	v_pk_fma_f32 v[242:243], v[106:107], v[106:107], v[242:243]
	v_mfma_f32_16x16x32_bf16 v[58:61], v[156:159], v[190:193], v[58:61]
	v_pk_add_f32 v[240:241], v[240:241], v[108:109]
	v_pk_fma_f32 v[242:243], v[108:109], v[108:109], v[242:243]
	v_pk_add_f32 v[240:241], v[240:241], v[102:103]
	v_pk_fma_f32 v[242:243], v[102:103], v[102:103], v[242:243]
	v_pk_add_f32 v[240:241], v[240:241], v[104:105]
	v_mfma_f32_16x16x32_bf16 v[46:49], v[134:137], v[198:201], v[46:49]
	v_pk_fma_f32 v[242:243], v[104:105], v[104:105], v[242:243]
	v_pk_add_f32 v[240:241], v[240:241], v[98:99]
	v_pk_fma_f32 v[242:243], v[98:99], v[98:99], v[242:243]
	v_pk_add_f32 v[240:241], v[240:241], v[100:101]
	v_pk_fma_f32 v[242:243], v[100:101], v[100:101], v[242:243]
	v_mfma_f32_16x16x32_bf16 v[42:45], v[156:159], v[198:201], v[42:45]
	v_add_f32_e32 v240, v240, v241
	v_add_f32_e32 v241, v242, v243
	v_mov_b32_e32 v242, v240
	v_mov_b32_e32 v243, v241
	s_nop 1
	v_permlane16_swap_b32_e32 v242, v240
	v_permlane16_swap_b32_e32 v243, v241
	v_mfma_f32_16x16x32_bf16 v[30:33], v[134:137], v[206:209], v[30:33]
	v_pk_add_f32 v[240:241], v[240:241], v[242:243]
	v_mov_b32_e32 v242, v240
	v_mov_b32_e32 v243, v241
	s_nop 1
	v_permlane32_swap_b32_e32 v242, v240
	v_permlane32_swap_b32_e32 v243, v241
	v_pk_add_f32 v[244:245], v[240:241], v[242:243]
	v_mfma_f32_16x16x32_bf16 v[26:29], v[156:159], v[206:209], v[26:29]
	v_cvt_pk_bf16_f32 v232, v110, v111
	v_cvt_pk_bf16_f32 v233, v112, v113
	v_cvt_pk_bf16_f32 v234, v106, v107
	v_cvt_pk_bf16_f32 v235, v108, v109
	global_store_dwordx4 v218, v[232:235], s[96:97]
	s_add_u32 s96, s96, 0x1000
	s_addc_u32 s97, s97, 0
	v_mfma_f32_16x16x32_bf16 v[14:17], v[134:137], v[214:217], v[14:17]
	v_cvt_pk_bf16_f32 v236, v102, v103
	v_cvt_pk_bf16_f32 v237, v104, v105
	v_cvt_pk_bf16_f32 v238, v98, v99
	v_cvt_pk_bf16_f32 v239, v100, v101
	global_store_dwordx4 v218, v[236:239], s[96:97]
	s_add_u32 s96, s96, 0x1000
	s_addc_u32 s97, s97, 0
	v_mfma_f32_16x16x32_bf16 v[10:13], v[156:159], v[214:217], v[10:13]
	s_and_saveexec_b64 vcc, s[0:1]
	global_store_dwordx2 v219, v[244:245], s[98:99]
	s_or_b64 exec, exec, vcc
	s_add_u32 s98, s98, 0x800
	s_addc_u32 s99, s99, 0
	v_mov_b32_e32 v240, v94
	v_mov_b32_e32 v241, v95
	v_pk_mul_f32 v[242:243], v[94:95], v[94:95]
	v_pk_add_f32 v[240:241], v[240:241], v[96:97]
	s_setprio 0
	s_setprio 1
	v_mfma_f32_16x16x32_bf16 v[54:57], v[166:169], v[186:189], v[54:57]
	v_pk_fma_f32 v[242:243], v[96:97], v[96:97], v[242:243]
	v_pk_add_f32 v[240:241], v[240:241], v[90:91]
	v_pk_fma_f32 v[242:243], v[90:91], v[90:91], v[242:243]
	v_pk_add_f32 v[240:241], v[240:241], v[92:93]
	v_pk_fma_f32 v[242:243], v[92:93], v[92:93], v[242:243]
	v_mfma_f32_16x16x32_bf16 v[50:53], v[174:177], v[186:189], v[50:53]
	v_pk_add_f32 v[240:241], v[240:241], v[86:87]
	v_pk_fma_f32 v[242:243], v[86:87], v[86:87], v[242:243]
	v_pk_add_f32 v[240:241], v[240:241], v[88:89]
	v_pk_fma_f32 v[242:243], v[88:89], v[88:89], v[242:243]
	v_pk_add_f32 v[240:241], v[240:241], v[82:83]
	v_mfma_f32_16x16x32_bf16 v[38:41], v[166:169], v[194:197], v[38:41]
	v_pk_fma_f32 v[242:243], v[82:83], v[82:83], v[242:243]
	v_pk_add_f32 v[240:241], v[240:241], v[84:85]
	v_pk_fma_f32 v[242:243], v[84:85], v[84:85], v[242:243]
	v_add_f32_e32 v240, v240, v241
	v_add_f32_e32 v241, v242, v243
	v_mfma_f32_16x16x32_bf16 v[34:37], v[174:177], v[194:197], v[34:37]
	v_mov_b32_e32 v242, v240
	v_mov_b32_e32 v243, v241
	s_nop 1
	v_permlane16_swap_b32_e32 v242, v240
	v_permlane16_swap_b32_e32 v243, v241
	v_pk_add_f32 v[240:241], v[240:241], v[242:243]
	v_mov_b32_e32 v242, v240
	v_mfma_f32_16x16x32_bf16 v[22:25], v[166:169], v[202:205], v[22:25]
	v_mov_b32_e32 v243, v241
	s_nop 1
	v_permlane32_swap_b32_e32 v242, v240
	v_permlane32_swap_b32_e32 v243, v241
	v_pk_add_f32 v[244:245], v[240:241], v[242:243]
	v_cvt_pk_bf16_f32 v232, v94, v95
	v_cvt_pk_bf16_f32 v233, v96, v97
	v_mfma_f32_16x16x32_bf16 v[18:21], v[174:177], v[202:205], v[18:21]
	v_cvt_pk_bf16_f32 v234, v90, v91
	v_cvt_pk_bf16_f32 v235, v92, v93
	global_store_dwordx4 v218, v[232:235], s[96:97]
	s_add_u32 s96, s96, 0x1000
	s_addc_u32 s97, s97, 0
	v_cvt_pk_bf16_f32 v236, v86, v87
	v_cvt_pk_bf16_f32 v237, v88, v89
	v_mfma_f32_16x16x32_bf16 v[6:9], v[166:169], v[210:213], v[6:9]
	v_cvt_pk_bf16_f32 v238, v82, v83
	v_cvt_pk_bf16_f32 v239, v84, v85
	global_store_dwordx4 v218, v[236:239], s[96:97]
	s_add_u32 s96, s96, 0x1000
	s_addc_u32 s97, s97, 0
	s_and_saveexec_b64 vcc, s[0:1]
	global_store_dwordx2 v219, v[244:245], s[98:99]
	s_or_b64 exec, exec, vcc
	s_add_u32 s98, s98, 0x800
	s_addc_u32 s99, s99, 0
; __device__ __forceinline__ unsigned cvt_pk_bf16(float lo, float hi) { unsigned r; asm volatile("v_cvt_pk_bf16_f32 %0, %1, %2" : "=v"(r) : "v"(lo), "v"(hi)); return r; }
; #define PG8_BAR __builtin_amdgcn_s_barrier()
; template <class Epi, class Sched, bool ALIGN_EPI = false, bool SP2 = false, bool RS = false, bool BPRE = false>
; __device__ __forceinline__ void gemm_phase(PG8_LAS unsigned char* lds, const Gemm g, const Sched& S, const Epi& E, const float* rs_ss = nullptr, PG8_LAS float* rs_tab = nullptr) {
;     ...
;         if constexpr (ALIGN_EPI) { if (wr == 0) PG8_BAR; }
;     __device__ __forceinline__ void operator()(const f32x4 (&acc)[2][2][4][2], const pg8::Unit& u, int wr, int wc, int fr, int fq, const LAS float* tab) const {
;     ...
;                     else if (kind == 3) {
; #pragma unroll
;                         for (int e = 0; e < 4; ++e) { s1 += v0[e] + v1[e]; s2 += v0[e] * v0[e] + v1[e] * v1[e]; }
;                     } else if (kind == 4) {
;                         v0 = v0 * f2; v1 = v1 * f2;
; #pragma unroll
;                         for (int e = 0; e < 4; ++e) s2 += v0[e] * v0[e] + v1[e] * v1[e];
;                     }
;                     u32x4 w; w.x = cvt_pk_bf16(v0[0], v0[1]); w.y = cvt_pk_bf16(v0[2], v0[3]); w.z = cvt_pk_bf16(v1[0], v1[1]); w.w = cvt_pk_bf16(v1[2], v1[3]);
;                     *(u32x4*)(rowp + bj * bjstep) = w;
;                 }
;                 if (kind == 3) {
;                     s1 += __shfl_xor(s1, 16); s1 += __shfl_xor(s1, 32); s2 += __shfl_xor(s2, 16); s2 += __shfl_xor(s2, 32);
;                     if (fq == 0) { float* p = aux + (size_t)row * 32 + ((pn - 12) * 4 + wc) * 2; p[0] = s1; p[1] = s2; }
	v_mov_b32_e32 v240, v78
	v_mfma_f32_16x16x32_bf16 v[2:5], v[174:177], v[210:213], v[2:5]
	v_mov_b32_e32 v241, v79
	v_pk_mul_f32 v[242:243], v[78:79], v[78:79]
	v_pk_add_f32 v[240:241], v[240:241], v[80:81]
	v_pk_fma_f32 v[242:243], v[80:81], v[80:81], v[242:243]
	v_pk_add_f32 v[240:241], v[240:241], v[74:75]
	v_mfma_f32_16x16x32_bf16 v[54:57], v[170:173], v[190:193], v[54:57]
	v_pk_fma_f32 v[242:243], v[74:75], v[74:75], v[242:243]
	v_pk_add_f32 v[240:241], v[240:241], v[76:77]
	v_pk_fma_f32 v[242:243], v[76:77], v[76:77], v[242:243]
	v_pk_add_f32 v[240:241], v[240:241], v[70:71]
	v_mfma_f32_16x16x32_bf16 v[50:53], v[182:185], v[190:193], v[50:53]
	v_pk_fma_f32 v[242:243], v[70:71], v[70:71], v[242:243]
	v_pk_add_f32 v[240:241], v[240:241], v[72:73]
	v_pk_fma_f32 v[242:243], v[72:73], v[72:73], v[242:243]
	v_pk_add_f32 v[240:241], v[240:241], v[66:67]
	v_mfma_f32_16x16x32_bf16 v[38:41], v[170:173], v[198:201], v[38:41]
	v_pk_fma_f32 v[242:243], v[66:67], v[66:67], v[242:243]
	v_pk_add_f32 v[240:241], v[240:241], v[68:69]
	v_pk_fma_f32 v[242:243], v[68:69], v[68:69], v[242:243]
	v_add_f32_e32 v240, v240, v241
	v_mfma_f32_16x16x32_bf16 v[34:37], v[182:185], v[198:201], v[34:37]
	v_add_f32_e32 v241, v242, v243
	v_mov_b32_e32 v242, v240
	v_mov_b32_e32 v243, v241
	s_nop 1
	v_permlane16_swap_b32_e32 v242, v240
	v_permlane16_swap_b32_e32 v243, v241
	v_mfma_f32_16x16x32_bf16 v[22:25], v[170:173], v[206:209], v[22:25]
	v_pk_add_f32 v[240:241], v[240:241], v[242:243]
	v_mov_b32_e32 v242, v240
	v_mov_b32_e32 v243, v241
	s_nop 1
	v_permlane32_swap_b32_e32 v242, v240
	v_permlane32_swap_b32_e32 v243, v241
	v_mfma_f32_16x16x32_bf16 v[18:21], v[182:185], v[206:209], v[18:21]
	v_pk_add_f32 v[244:245], v[240:241], v[242:243]
	v_cvt_pk_bf16_f32 v232, v78, v79
	v_cvt_pk_bf16_f32 v233, v80, v81
	v_cvt_pk_bf16_f32 v234, v74, v75
	v_mfma_f32_16x16x32_bf16 v[6:9], v[170:173], v[214:217], v[6:9]
	v_cvt_pk_bf16_f32 v235, v76, v77
	global_store_dwordx4 v218, v[232:235], s[96:97]
	s_add_u32 s96, s96, 0x1000
	s_addc_u32 s97, s97, 0
	v_cvt_pk_bf16_f32 v236, v70, v71
	v_cvt_pk_bf16_f32 v237, v72, v73
	v_mfma_f32_16x16x32_bf16 v[2:5], v[182:185], v[214:217], v[2:5]
	v_cvt_pk_bf16_f32 v238, v66, v67
	v_cvt_pk_bf16_f32 v239, v68, v69
	global_store_dwordx4 v218, v[236:239], s[96:97]
	s_add_u32 s96, s96, 0x1000
	s_addc_u32 s97, s97, 0
	s_add_u32 s96, s96, 0x8000
	s_addc_u32 s97, s97, 0
	s_and_saveexec_b64 vcc, s[0:1]
	global_store_dwordx2 v219, v[244:245], s[98:99]
	s_or_b64 exec, exec, vcc
	s_add_u32 s98, s98, 0x2800
	s_addc_u32 s99, s99, 0
	s_setprio 0
	s_barrier
	s_add_i32 s89, s89, 2
	s_add_u32 s56, s56, 0x8000
	s_addc_u32 s57, s57, 0
	s_add_u32 s87, s87, 0x8000
	s_addc_u32 s88, s88, 0
	s_and_b64 vcc, exec, s[12:13]
	s_cbranch_vccz .Lepi_stats_al
	s_barrier
.Lepi_stats_al:
	v_mov_b32_e32 v240, v62
	v_mov_b32_e32 v241, v63
	v_pk_mul_f32 v[242:243], v[62:63], v[62:63]
	v_pk_add_f32 v[240:241], v[240:241], v[64:65]
	v_pk_fma_f32 v[242:243], v[64:65], v[64:65], v[242:243]
	v_pk_add_f32 v[240:241], v[240:241], v[58:59]
	v_pk_fma_f32 v[242:243], v[58:59], v[58:59], v[242:243]
	v_pk_add_f32 v[240:241], v[240:241], v[60:61]
	v_pk_fma_f32 v[242:243], v[60:61], v[60:61], v[242:243]
	v_pk_add_f32 v[240:241], v[240:241], v[54:55]
	v_pk_fma_f32 v[242:243], v[54:55], v[54:55], v[242:243]
	v_pk_add_f32 v[240:241], v[240:241], v[56:57]
	v_pk_fma_f32 v[242:243], v[56:57], v[56:57], v[242:243]
	v_pk_add_f32 v[240:241], v[240:241], v[50:51]
	v_pk_fma_f32 v[242:243], v[50:51], v[50:51], v[242:243]
	v_pk_add_f32 v[240:241], v[240:241], v[52:53]
	v_pk_fma_f32 v[242:243], v[52:53], v[52:53], v[242:243]
	v_add_f32_e32 v240, v240, v241
	v_add_f32_e32 v241, v242, v243
	v_mov_b32_e32 v242, v240
	v_mov_b32_e32 v243, v241
	s_nop 1
	v_permlane16_swap_b32_e32 v242, v240
	v_permlane16_swap_b32_e32 v243, v241
	v_pk_add_f32 v[240:241], v[240:241], v[242:243]
	v_mov_b32_e32 v242, v240
	v_mov_b32_e32 v243, v241
	s_nop 1
	v_permlane32_swap_b32_e32 v242, v240
	v_permlane32_swap_b32_e32 v243, v241
	v_pk_add_f32 v[244:245], v[240:241], v[242:243]
	v_cvt_pk_bf16_f32 v232, v62, v63
	v_cvt_pk_bf16_f32 v233, v64, v65
	v_cvt_pk_bf16_f32 v234, v58, v59
	v_cvt_pk_bf16_f32 v235, v60, v61
	global_store_dwordx4 v218, v[232:235], s[96:97]
	s_add_u32 s96, s96, 0x1000
	s_addc_u32 s97, s97, 0
	v_cvt_pk_bf16_f32 v236, v54, v55
	v_cvt_pk_bf16_f32 v237, v56, v57
	v_cvt_pk_bf16_f32 v238, v50, v51
	v_cvt_pk_bf16_f32 v239, v52, v53
	global_store_dwordx4 v218, v[236:239], s[96:97]
	s_add_u32 s96, s96, 0x1000
	s_addc_u32 s97, s97, 0
	s_and_saveexec_b64 vcc, s[0:1]
	global_store_dwordx2 v219, v[244:245], s[98:99]
	s_or_b64 exec, exec, vcc
	s_add_u32 s98, s98, 0x800
	s_addc_u32 s99, s99, 0
	v_mov_b32_e32 v240, v46
	v_mov_b32_e32 v241, v47
	v_pk_mul_f32 v[242:243], v[46:47], v[46:47]
	v_pk_add_f32 v[240:241], v[240:241], v[48:49]
	v_pk_fma_f32 v[242:243], v[48:49], v[48:49], v[242:243]
	v_pk_add_f32 v[240:241], v[240:241], v[42:43]
	v_pk_fma_f32 v[242:243], v[42:43], v[42:43], v[242:243]
	v_pk_add_f32 v[240:241], v[240:241], v[44:45]
	v_pk_fma_f32 v[242:243], v[44:45], v[44:45], v[242:243]
	v_pk_add_f32 v[240:241], v[240:241], v[38:39]
	v_pk_fma_f32 v[242:243], v[38:39], v[38:39], v[242:243]
; __device__ __forceinline__ unsigned cvt_pk_bf16(float lo, float hi) { unsigned r; asm volatile("v_cvt_pk_bf16_f32 %0, %1, %2" : "=v"(r) : "v"(lo), "v"(hi)); return r; }
;     __device__ __forceinline__ void operator()(const f32x4 (&acc)[2][2][4][2], const pg8::Unit& u, int wr, int wc, int fr, int fq, const LAS float* tab) const {
;     ...
;                     else if (kind == 3) {
; #pragma unroll
;                         for (int e = 0; e < 4; ++e) { s1 += v0[e] + v1[e]; s2 += v0[e] * v0[e] + v1[e] * v1[e]; }
;                     } else if (kind == 4) {
;                         v0 = v0 * f2; v1 = v1 * f2;
; #pragma unroll
;                         for (int e = 0; e < 4; ++e) s2 += v0[e] * v0[e] + v1[e] * v1[e];
;                     }
;                     u32x4 w; w.x = cvt_pk_bf16(v0[0], v0[1]); w.y = cvt_pk_bf16(v0[2], v0[3]); w.z = cvt_pk_bf16(v1[0], v1[1]); w.w = cvt_pk_bf16(v1[2], v1[3]);
;                     *(u32x4*)(rowp + bj * bjstep) = w;
;                 }
;                 if (kind == 3) {
;                     s1 += __shfl_xor(s1, 16); s1 += __shfl_xor(s1, 32); s2 += __shfl_xor(s2, 16); s2 += __shfl_xor(s2, 32);
;                     if (fq == 0) { float* p = aux + (size_t)row * 32 + ((pn - 12) * 4 + wc) * 2; p[0] = s1; p[1] = s2; }
	v_pk_add_f32 v[240:241], v[240:241], v[40:41]
	v_pk_fma_f32 v[242:243], v[40:41], v[40:41], v[242:243]
	v_pk_add_f32 v[240:241], v[240:241], v[34:35]
	v_pk_fma_f32 v[242:243], v[34:35], v[34:35], v[242:243]
	v_pk_add_f32 v[240:241], v[240:241], v[36:37]
	v_pk_fma_f32 v[242:243], v[36:37], v[36:37], v[242:243]
	v_add_f32_e32 v240, v240, v241
	v_add_f32_e32 v241, v242, v243
	v_mov_b32_e32 v242, v240
	v_mov_b32_e32 v243, v241
	s_nop 1
	v_permlane16_swap_b32_e32 v242, v240
	v_permlane16_swap_b32_e32 v243, v241
	v_pk_add_f32 v[240:241], v[240:241], v[242:243]
	v_mov_b32_e32 v242, v240
	v_mov_b32_e32 v243, v241
	s_nop 1
	v_permlane32_swap_b32_e32 v242, v240
	v_permlane32_swap_b32_e32 v243, v241
	v_pk_add_f32 v[244:245], v[240:241], v[242:243]
	v_cvt_pk_bf16_f32 v232, v46, v47
	v_cvt_pk_bf16_f32 v233, v48, v49
	v_cvt_pk_bf16_f32 v234, v42, v43
	v_cvt_pk_bf16_f32 v235, v44, v45
	global_store_dwordx4 v218, v[232:235], s[96:97]
	s_add_u32 s96, s96, 0x1000
	s_addc_u32 s97, s97, 0
	v_cvt_pk_bf16_f32 v236, v38, v39
	v_cvt_pk_bf16_f32 v237, v40, v41
	v_cvt_pk_bf16_f32 v238, v34, v35
	v_cvt_pk_bf16_f32 v239, v36, v37
	global_store_dwordx4 v218, v[236:239], s[96:97]
	s_add_u32 s96, s96, 0x1000
	s_addc_u32 s97, s97, 0
	s_and_saveexec_b64 vcc, s[0:1]
	global_store_dwordx2 v219, v[244:245], s[98:99]
	s_or_b64 exec, exec, vcc
	s_add_u32 s98, s98, 0x800
	s_addc_u32 s99, s99, 0
	v_mov_b32_e32 v240, v30
	v_mov_b32_e32 v241, v31
	v_pk_mul_f32 v[242:243], v[30:31], v[30:31]
	v_pk_add_f32 v[240:241], v[240:241], v[32:33]
	v_pk_fma_f32 v[242:243], v[32:33], v[32:33], v[242:243]
	v_pk_add_f32 v[240:241], v[240:241], v[26:27]
	v_pk_fma_f32 v[242:243], v[26:27], v[26:27], v[242:243]
	v_pk_add_f32 v[240:241], v[240:241], v[28:29]
	v_pk_fma_f32 v[242:243], v[28:29], v[28:29], v[242:243]
	v_pk_add_f32 v[240:241], v[240:241], v[22:23]
	v_pk_fma_f32 v[242:243], v[22:23], v[22:23], v[242:243]
	v_pk_add_f32 v[240:241], v[240:241], v[24:25]
	v_pk_fma_f32 v[242:243], v[24:25], v[24:25], v[242:243]
	v_pk_add_f32 v[240:241], v[240:241], v[18:19]
	v_pk_fma_f32 v[242:243], v[18:19], v[18:19], v[242:243]
	v_pk_add_f32 v[240:241], v[240:241], v[20:21]
	v_pk_fma_f32 v[242:243], v[20:21], v[20:21], v[242:243]
	v_add_f32_e32 v240, v240, v241
	v_add_f32_e32 v241, v242, v243
	v_mov_b32_e32 v242, v240
	v_mov_b32_e32 v243, v241
	s_nop 1
	v_permlane16_swap_b32_e32 v242, v240
	v_permlane16_swap_b32_e32 v243, v241
	v_pk_add_f32 v[240:241], v[240:241], v[242:243]
	v_mov_b32_e32 v242, v240
	v_mov_b32_e32 v243, v241
	s_nop 1
	v_permlane32_swap_b32_e32 v242, v240
	v_permlane32_swap_b32_e32 v243, v241
	v_pk_add_f32 v[244:245], v[240:241], v[242:243]
	v_cvt_pk_bf16_f32 v232, v30, v31
	v_cvt_pk_bf16_f32 v233, v32, v33
	v_cvt_pk_bf16_f32 v234, v26, v27
	v_cvt_pk_bf16_f32 v235, v28, v29
	global_store_dwordx4 v218, v[232:235], s[96:97]
	s_add_u32 s96, s96, 0x1000
	s_addc_u32 s97, s97, 0
	v_cvt_pk_bf16_f32 v236, v22, v23
	v_cvt_pk_bf16_f32 v237, v24, v25
	v_cvt_pk_bf16_f32 v238, v18, v19
	v_cvt_pk_bf16_f32 v239, v20, v21
	global_store_dwordx4 v218, v[236:239], s[96:97]
	s_add_u32 s96, s96, 0x1000
	s_addc_u32 s97, s97, 0
	s_and_saveexec_b64 vcc, s[0:1]
	global_store_dwordx2 v219, v[244:245], s[98:99]
	s_or_b64 exec, exec, vcc
	s_add_u32 s98, s98, 0x800
	s_addc_u32 s99, s99, 0
	v_mov_b32_e32 v240, v14
	v_mov_b32_e32 v241, v15
	v_pk_mul_f32 v[242:243], v[14:15], v[14:15]
	v_pk_add_f32 v[240:241], v[240:241], v[16:17]
	v_pk_fma_f32 v[242:243], v[16:17], v[16:17], v[242:243]
	v_pk_add_f32 v[240:241], v[240:241], v[10:11]
	v_pk_fma_f32 v[242:243], v[10:11], v[10:11], v[242:243]
	v_pk_add_f32 v[240:241], v[240:241], v[12:13]
	v_pk_fma_f32 v[242:243], v[12:13], v[12:13], v[242:243]
	v_pk_add_f32 v[240:241], v[240:241], v[6:7]
	v_pk_fma_f32 v[242:243], v[6:7], v[6:7], v[242:243]
	v_pk_add_f32 v[240:241], v[240:241], v[8:9]
	v_pk_fma_f32 v[242:243], v[8:9], v[8:9], v[242:243]
	v_pk_add_f32 v[240:241], v[240:241], v[2:3]
	v_pk_fma_f32 v[242:243], v[2:3], v[2:3], v[242:243]
	v_pk_add_f32 v[240:241], v[240:241], v[4:5]
	v_pk_fma_f32 v[242:243], v[4:5], v[4:5], v[242:243]
	v_add_f32_e32 v240, v240, v241
	v_add_f32_e32 v241, v242, v243
	v_mov_b32_e32 v242, v240
	v_mov_b32_e32 v243, v241
	s_nop 1
	v_permlane16_swap_b32_e32 v242, v240
	v_permlane16_swap_b32_e32 v243, v241
	v_pk_add_f32 v[240:241], v[240:241], v[242:243]
	v_mov_b32_e32 v242, v240
	v_mov_b32_e32 v243, v241
	s_nop 1
	v_permlane32_swap_b32_e32 v242, v240
	v_permlane32_swap_b32_e32 v243, v241
	v_pk_add_f32 v[244:245], v[240:241], v[242:243]
	v_cvt_pk_bf16_f32 v232, v14, v15
	v_cvt_pk_bf16_f32 v233, v16, v17
	v_cvt_pk_bf16_f32 v234, v10, v11
	v_cvt_pk_bf16_f32 v235, v12, v13
	global_store_dwordx4 v218, v[232:235], s[96:97]
	s_add_u32 s96, s96, 0x1000
	s_addc_u32 s97, s97, 0
	v_cvt_pk_bf16_f32 v236, v6, v7
	v_cvt_pk_bf16_f32 v237, v8, v9
	v_cvt_pk_bf16_f32 v238, v2, v3
	v_cvt_pk_bf16_f32 v239, v4, v5
	global_store_dwordx4 v218, v[236:239], s[96:97]
	s_add_u32 s96, s96, 0x1000
	s_addc_u32 s97, s97, 0
	s_and_saveexec_b64 vcc, s[0:1]
	global_store_dwordx2 v219, v[244:245], s[98:99]
	s_or_b64 exec, exec, vcc
	s_add_u32 s98, s98, 0x800
	s_addc_u32 s99, s99, 0
	s_branch .LBB0_391
